# SwiGLU epilogue packed f32 ops split into scalar pairs (bit-identical), to price v_pk ops
# speedup vs baseline: 1.0013x; 1.0013x over previous
; __device__ __forceinline__ unsigned cvtpk(float lo, float hi) { f32x2v_ v = {lo, hi}; bf16x2v_ b = __builtin_convertvector(v, bf16x2v_); return __builtin_bit_cast(unsigned, b); }
; __device__ __forceinline__ float row_rs(const float* ssp, int row) { const unsigned long long v = ((const unsigned long long*)ssp)[row];
;     return __builtin_amdgcn_rsqf((float)v * (1.0f / 4294967296.0f) * (1.0f / 1024.0f) + RMS_EPS); }
;     __device__ __forceinline__ void operator()(const f32x4 (&acc)[2][2][4][2], const Unit& u, int wr, int wc, int fr, int fq) const {
;     ...
;             for (int m = 0; m < 4; ++m) { const int row = row0 + ai * HALF + m * 16; const float rs = row_rs(ss, row);
;                 float hv[8];
; #pragma unroll
;                 for (int n = 0; n < 2; ++n)
; #pragma unroll
;                     for (int i = 0; i < 4; ++i) { const float g = acc[ai][0][m][n][i] * rs, uu = acc[ai][1][m][n][i] * rs;
;                         hv[n * 4 + i] = g * __builtin_amdgcn_rcpf(1.0f + __expf(-g)) * uu; }
;                 u32x4 w; w.x = cvtpk(hv[0], hv[1]); w.y = cvtpk(hv[2], hv[3]); w.z = cvtpk(hv[4], hv[5]); w.w = cvtpk(hv[6], hv[7]);
;                 *(u32x4*)(H + (size_t)row * ldh + col0) = w; }
.LBB0_194:
	v_lshl_or_b32 v160, s66, 7, v154
	v_ashrrev_i32_e32 v161, 31, v160
	v_or_b32_e32 v164, 16, v144
	v_ashrrev_i32_e32 v165, 31, v164
	v_lshl_add_u64 v[168:169], v[164:165], 3, s[6:7]
	v_mov_b64_e32 v[146:147], s[20:21]
	v_mad_i64_i32 v[162:163], s[14:15], v144, s65, v[146:147]
	s_andn2_b64 vcc, exec, s[0:1]
	s_mov_b64 s[0:1], -1
	s_waitcnt vmcnt(7)
	v_cvt_f32_u32_e32 v159, v183
	v_cvt_f32_u32_e32 v145, v182
	v_lshlrev_b64 v[148:149], 1, v[160:161]
	v_lshl_add_u64 v[162:163], v[162:163], 0, v[148:149]
	v_fmamk_f32 v145, v145, 0x2f800000, v159
	v_fmamk_f32 v145, v145, 0x3a800000, v158
	v_rsq_f32_e32 v160, v145
	s_nop 0
	v_mul_f32_e32 v182, 0xbfb8aa3b, v160
	v_mul_f32_e32 v183, v160, v160
	v_mul_f32_e32 v160, v124, v182
	v_mul_f32_e32 v161, v125, v182
	v_mul_f32_e32 v170, v126, v182
	v_mul_f32_e32 v171, v127, v182
	v_mul_f32_e32 v172, v120, v182
	v_mul_f32_e32 v173, v121, v182
	v_mul_f32_e32 v174, v122, v182
	v_mul_f32_e32 v175, v123, v182
	v_mul_f32_e32 v116, v116, v124
	v_mul_f32_e32 v117, v117, v125
	v_mul_f32_e32 v118, v118, v126
	v_mul_f32_e32 v119, v119, v127
	v_mul_f32_e32 v120, v112, v120
	v_mul_f32_e32 v121, v113, v121
	v_mul_f32_e32 v122, v114, v122
	v_mul_f32_e32 v123, v115, v123
	v_exp_f32_e32 v160, v160
	v_exp_f32_e32 v161, v161
	v_exp_f32_e32 v170, v170
	v_exp_f32_e32 v171, v171
	v_exp_f32_e32 v172, v172
	v_exp_f32_e32 v173, v173
	v_exp_f32_e32 v174, v174
	v_exp_f32_e32 v175, v175
	v_mul_f32_e32 v116, v116, v183
	v_mul_f32_e32 v117, v117, v183
	v_mul_f32_e32 v118, v118, v183
	v_mul_f32_e32 v119, v119, v183
	v_mul_f32_e32 v120, v120, v183
	v_mul_f32_e32 v121, v121, v183
	v_mul_f32_e32 v122, v122, v183
	v_mul_f32_e32 v123, v123, v183
	v_add_f32_e32 v160, 1.0, v160
	v_add_f32_e32 v161, 1.0, v161
	v_add_f32_e32 v170, 1.0, v170
	v_add_f32_e32 v171, 1.0, v171
	v_add_f32_e32 v172, 1.0, v172
	v_add_f32_e32 v173, 1.0, v173
	v_add_f32_e32 v174, 1.0, v174
	v_add_f32_e32 v175, 1.0, v175
	v_rcp_f32_e32 v160, v160
	v_rcp_f32_e32 v161, v161
	v_rcp_f32_e32 v170, v170
	v_rcp_f32_e32 v171, v171
	v_rcp_f32_e32 v172, v172
	v_rcp_f32_e32 v173, v173
	v_rcp_f32_e32 v174, v174
	v_rcp_f32_e32 v175, v175
	v_mul_f32_e32 v116, v116, v160
	v_mul_f32_e32 v117, v117, v161
	v_mul_f32_e32 v118, v118, v170
	v_mul_f32_e32 v119, v119, v171
	v_mul_f32_e32 v120, v120, v172
	v_mul_f32_e32 v121, v121, v173
	v_mul_f32_e32 v122, v122, v174
	v_mul_f32_e32 v123, v123, v175
	v_cvt_pk_bf16_f32 v112, v116, v117
	v_cvt_pk_bf16_f32 v113, v118, v119
	v_cvt_pk_bf16_f32 v114, v120, v121
	v_cvt_pk_bf16_f32 v115, v122, v123
	global_store_dwordx4 v[162:163], v[112:115], off
	s_nop 0
	s_nop 0
	v_or_b32_e32 v114, 32, v144
	s_waitcnt vmcnt(7)
	v_cvt_f32_u32_e32 v116, v185
	v_cvt_f32_u32_e32 v115, v184
	v_mad_i64_i32 v[112:113], s[14:15], v164, s65, v[146:147]
	v_fmamk_f32 v115, v115, 0x2f800000, v116
	v_fmamk_f32 v115, v115, 0x3a800000, v158
	v_rsq_f32_e32 v116, v115
	v_ashrrev_i32_e32 v115, 31, v114
	v_lshl_add_u64 v[118:119], v[114:115], 3, s[6:7]
	v_lshl_add_u64 v[112:113], v[112:113], 0, v[148:149]
	v_mul_f32_e32 v184, 0xbfb8aa3b, v116
	v_mul_f32_e32 v185, v116, v116
	v_mul_f32_e32 v116, v108, v184
	v_mul_f32_e32 v117, v109, v184
	v_mul_f32_e32 v120, v110, v184
	v_mul_f32_e32 v121, v111, v184
	v_mul_f32_e32 v122, v104, v184
	v_mul_f32_e32 v123, v105, v184
	v_mul_f32_e32 v124, v106, v184
	v_mul_f32_e32 v125, v107, v184
	v_mul_f32_e32 v100, v100, v108
	v_mul_f32_e32 v101, v101, v109
	v_mul_f32_e32 v102, v102, v110
	v_mul_f32_e32 v103, v103, v111
	v_mul_f32_e32 v104, v96, v104
	v_mul_f32_e32 v105, v97, v105
	v_mul_f32_e32 v106, v98, v106
	v_mul_f32_e32 v107, v99, v107
	v_exp_f32_e32 v116, v116
	v_exp_f32_e32 v117, v117
	v_exp_f32_e32 v120, v120
	v_exp_f32_e32 v121, v121
	v_exp_f32_e32 v122, v122
	v_exp_f32_e32 v123, v123
	v_exp_f32_e32 v124, v124
	v_exp_f32_e32 v125, v125
	v_mul_f32_e32 v100, v100, v185
	v_mul_f32_e32 v101, v101, v185
	v_mul_f32_e32 v102, v102, v185
	v_mul_f32_e32 v103, v103, v185
	v_mul_f32_e32 v104, v104, v185
	v_mul_f32_e32 v105, v105, v185
	v_mul_f32_e32 v106, v106, v185
	v_mul_f32_e32 v107, v107, v185
	v_add_f32_e32 v116, 1.0, v116
	v_add_f32_e32 v117, 1.0, v117
	v_add_f32_e32 v120, 1.0, v120
	v_add_f32_e32 v121, 1.0, v121
	v_add_f32_e32 v122, 1.0, v122
	v_add_f32_e32 v123, 1.0, v123
	v_add_f32_e32 v124, 1.0, v124
	v_add_f32_e32 v125, 1.0, v125
	v_rcp_f32_e32 v116, v116
	v_rcp_f32_e32 v117, v117
	v_rcp_f32_e32 v120, v120
	v_rcp_f32_e32 v121, v121
	v_rcp_f32_e32 v122, v122
	v_rcp_f32_e32 v123, v123
	v_rcp_f32_e32 v124, v124
	v_rcp_f32_e32 v125, v125
	v_mul_f32_e32 v100, v100, v116
	v_mul_f32_e32 v101, v101, v117
	v_mul_f32_e32 v102, v102, v120
	v_mul_f32_e32 v103, v103, v121
	v_mul_f32_e32 v104, v104, v122
	v_mul_f32_e32 v105, v105, v123
	v_mul_f32_e32 v106, v106, v124
	v_mul_f32_e32 v107, v107, v125
	v_cvt_pk_bf16_f32 v96, v100, v101
	v_cvt_pk_bf16_f32 v97, v102, v103
	v_cvt_pk_bf16_f32 v98, v104, v105
	v_cvt_pk_bf16_f32 v99, v106, v107
	global_store_dwordx4 v[112:113], v[96:99], off
	s_nop 0
	s_nop 0
	v_or_b32_e32 v98, 48, v144
	s_waitcnt vmcnt(7)
; __device__ __forceinline__ unsigned cvtpk(float lo, float hi) { f32x2v_ v = {lo, hi}; bf16x2v_ b = __builtin_convertvector(v, bf16x2v_); return __builtin_bit_cast(unsigned, b); }
; __device__ __forceinline__ float row_rs(const float* ssp, int row) { const unsigned long long v = ((const unsigned long long*)ssp)[row];
;     return __builtin_amdgcn_rsqf((float)v * (1.0f / 4294967296.0f) * (1.0f / 1024.0f) + RMS_EPS); }
;     __device__ __forceinline__ void operator()(const f32x4 (&acc)[2][2][4][2], const Unit& u, int wr, int wc, int fr, int fq) const {
;     ...
;             for (int m = 0; m < 4; ++m) { const int row = row0 + ai * HALF + m * 16; const float rs = row_rs(ss, row);
;                 float hv[8];
; #pragma unroll
;                 for (int n = 0; n < 2; ++n)
; #pragma unroll
;                     for (int i = 0; i < 4; ++i) { const float g = acc[ai][0][m][n][i] * rs, uu = acc[ai][1][m][n][i] * rs;
;                         hv[n * 4 + i] = g * __builtin_amdgcn_rcpf(1.0f + __expf(-g)) * uu; }
;                 u32x4 w; w.x = cvtpk(hv[0], hv[1]); w.y = cvtpk(hv[2], hv[3]); w.z = cvtpk(hv[4], hv[5]); w.w = cvtpk(hv[6], hv[7]);
;                 *(u32x4*)(H + (size_t)row * ldh + col0) = w; }
	v_cvt_f32_u32_e32 v100, v187
	v_cvt_f32_u32_e32 v99, v186
	v_mad_i64_i32 v[96:97], s[14:15], v114, s65, v[146:147]
	v_fmamk_f32 v99, v99, 0x2f800000, v100
	v_fmamk_f32 v99, v99, 0x3a800000, v158
	v_rsq_f32_e32 v100, v99
	v_ashrrev_i32_e32 v99, 31, v98
	v_lshl_add_u64 v[102:103], v[98:99], 3, s[6:7]
	v_lshl_add_u64 v[96:97], v[96:97], 0, v[148:149]
	v_mul_f32_e32 v186, 0xbfb8aa3b, v100
	v_mul_f32_e32 v187, v100, v100
	v_mul_f32_e32 v100, v92, v186
	v_mul_f32_e32 v101, v93, v186
	v_mul_f32_e32 v104, v94, v186
	v_mul_f32_e32 v105, v95, v186
	v_mul_f32_e32 v106, v88, v186
	v_mul_f32_e32 v107, v89, v186
	v_mul_f32_e32 v108, v90, v186
	v_mul_f32_e32 v109, v91, v186
	v_mul_f32_e32 v84, v84, v92
	v_mul_f32_e32 v85, v85, v93
	v_mul_f32_e32 v86, v86, v94
	v_mul_f32_e32 v87, v87, v95
	v_mul_f32_e32 v88, v80, v88
	v_mul_f32_e32 v89, v81, v89
	v_mul_f32_e32 v90, v82, v90
	v_mul_f32_e32 v91, v83, v91
	v_exp_f32_e32 v100, v100
	v_exp_f32_e32 v101, v101
	v_exp_f32_e32 v104, v104
	v_exp_f32_e32 v105, v105
	v_exp_f32_e32 v106, v106
	v_exp_f32_e32 v107, v107
	v_exp_f32_e32 v108, v108
	v_exp_f32_e32 v109, v109
	v_mul_f32_e32 v84, v84, v187
	v_mul_f32_e32 v85, v85, v187
	v_mul_f32_e32 v86, v86, v187
	v_mul_f32_e32 v87, v87, v187
	v_mul_f32_e32 v88, v88, v187
	v_mul_f32_e32 v89, v89, v187
	v_mul_f32_e32 v90, v90, v187
	v_mul_f32_e32 v91, v91, v187
	v_add_f32_e32 v100, 1.0, v100
	v_add_f32_e32 v101, 1.0, v101
	v_add_f32_e32 v104, 1.0, v104
	v_add_f32_e32 v105, 1.0, v105
	v_add_f32_e32 v106, 1.0, v106
	v_add_f32_e32 v107, 1.0, v107
	v_add_f32_e32 v108, 1.0, v108
	v_add_f32_e32 v109, 1.0, v109
	v_rcp_f32_e32 v100, v100
	v_rcp_f32_e32 v101, v101
	v_rcp_f32_e32 v104, v104
	v_rcp_f32_e32 v105, v105
	v_rcp_f32_e32 v106, v106
	v_rcp_f32_e32 v107, v107
	v_rcp_f32_e32 v108, v108
	v_rcp_f32_e32 v109, v109
	v_mul_f32_e32 v84, v84, v100
	v_mul_f32_e32 v85, v85, v101
	v_mul_f32_e32 v86, v86, v104
	v_mul_f32_e32 v87, v87, v105
	v_mul_f32_e32 v88, v88, v106
	v_mul_f32_e32 v89, v89, v107
	v_mul_f32_e32 v90, v90, v108
	v_mul_f32_e32 v91, v91, v109
	v_cvt_pk_bf16_f32 v80, v84, v85
	v_cvt_pk_bf16_f32 v81, v86, v87
	v_cvt_pk_bf16_f32 v82, v88, v89
	v_cvt_pk_bf16_f32 v83, v90, v91
	global_store_dwordx4 v[96:97], v[80:83], off
	s_nop 0
	s_waitcnt vmcnt(7)
	v_cvt_f32_u32_e32 v80, v189
	v_cvt_f32_u32_e32 v81, v188
	v_mad_i64_i32 v[82:83], s[14:15], v98, s65, v[146:147]
	v_fmamk_f32 v80, v81, 0x2f800000, v80
	v_fmamk_f32 v80, v80, 0x3a800000, v158
	v_rsq_f32_e32 v80, v80
	v_lshl_add_u64 v[82:83], v[82:83], 0, v[148:149]
	v_mul_f32_e32 v188, 0xbfb8aa3b, v80
	v_mul_f32_e32 v189, v80, v80
	v_mul_f32_e32 v80, v76, v188
	v_mul_f32_e32 v81, v77, v188
	v_mul_f32_e32 v84, v78, v188
	v_mul_f32_e32 v85, v79, v188
	v_mul_f32_e32 v86, v72, v188
	v_mul_f32_e32 v87, v73, v188
	v_mul_f32_e32 v88, v74, v188
	v_mul_f32_e32 v89, v75, v188
	v_mul_f32_e32 v68, v68, v76
	v_mul_f32_e32 v69, v69, v77
	v_mul_f32_e32 v70, v70, v78
	v_mul_f32_e32 v71, v71, v79
	v_mul_f32_e32 v72, v64, v72
	v_mul_f32_e32 v73, v65, v73
	v_mul_f32_e32 v74, v66, v74
	v_mul_f32_e32 v75, v67, v75
	v_exp_f32_e32 v80, v80
	v_exp_f32_e32 v81, v81
	v_exp_f32_e32 v84, v84
	v_exp_f32_e32 v85, v85
	v_exp_f32_e32 v86, v86
	v_exp_f32_e32 v87, v87
	v_exp_f32_e32 v88, v88
	v_exp_f32_e32 v89, v89
	v_mul_f32_e32 v68, v68, v189
	v_mul_f32_e32 v69, v69, v189
	v_mul_f32_e32 v70, v70, v189
	v_mul_f32_e32 v71, v71, v189
	v_mul_f32_e32 v72, v72, v189
	v_mul_f32_e32 v73, v73, v189
	v_mul_f32_e32 v74, v74, v189
	v_mul_f32_e32 v75, v75, v189
	v_add_f32_e32 v80, 1.0, v80
	v_add_f32_e32 v81, 1.0, v81
	v_add_f32_e32 v84, 1.0, v84
	v_add_f32_e32 v85, 1.0, v85
	v_add_f32_e32 v86, 1.0, v86
	v_add_f32_e32 v87, 1.0, v87
	v_add_f32_e32 v88, 1.0, v88
	v_add_f32_e32 v89, 1.0, v89
	v_rcp_f32_e32 v80, v80
	v_rcp_f32_e32 v81, v81
	v_rcp_f32_e32 v84, v84
	v_rcp_f32_e32 v85, v85
	v_rcp_f32_e32 v86, v86
	v_rcp_f32_e32 v87, v87
	v_rcp_f32_e32 v88, v88
	v_rcp_f32_e32 v89, v89
	v_mul_f32_e32 v68, v68, v80
	v_mul_f32_e32 v69, v69, v81
	v_mul_f32_e32 v70, v70, v84
	v_mul_f32_e32 v71, v71, v85
	v_mul_f32_e32 v72, v72, v86
	v_mul_f32_e32 v73, v73, v87
	v_mul_f32_e32 v74, v74, v88
	v_mul_f32_e32 v75, v75, v89
	v_cvt_pk_bf16_f32 v64, v68, v69
	v_cvt_pk_bf16_f32 v65, v70, v71
	v_cvt_pk_bf16_f32 v66, v72, v73
	v_cvt_pk_bf16_f32 v67, v74, v75
	global_store_dwordx4 v[82:83], v[64:67], off
	s_nop 0
	s_waitcnt vmcnt(7)
	v_cvt_f32_u32_e32 v64, v191
	v_cvt_f32_u32_e32 v66, v190
	v_add_u32_e32 v65, 0x80, v144
	v_fmamk_f32 v64, v66, 0x2f800000, v64
	v_fmamk_f32 v64, v64, 0x3a800000, v158
	v_rsq_f32_e32 v64, v64
	v_mad_i64_i32 v[66:67], s[14:15], v65, s65, v[146:147]
	v_lshl_add_u64 v[66:67], v[66:67], 0, v[148:149]
	v_mul_f32_e32 v190, 0xbfb8aa3b, v64
	v_mul_f32_e32 v191, v64, v64
	v_mul_f32_e32 v64, v60, v190
	v_mul_f32_e32 v65, v61, v190
	v_mul_f32_e32 v68, v62, v190
	v_mul_f32_e32 v69, v63, v190
	v_mul_f32_e32 v70, v56, v190
	v_mul_f32_e32 v71, v57, v190
	v_mul_f32_e32 v72, v58, v190
	v_mul_f32_e32 v73, v59, v190
	v_mul_f32_e32 v52, v52, v60
	v_mul_f32_e32 v53, v53, v61
	v_mul_f32_e32 v54, v54, v62
	v_mul_f32_e32 v55, v55, v63
	v_mul_f32_e32 v56, v48, v56
	v_mul_f32_e32 v57, v49, v57
	v_mul_f32_e32 v58, v50, v58
	v_mul_f32_e32 v59, v51, v59
	v_exp_f32_e32 v64, v64
	v_exp_f32_e32 v65, v65
	v_exp_f32_e32 v68, v68
	v_exp_f32_e32 v69, v69
	v_exp_f32_e32 v70, v70
	v_exp_f32_e32 v71, v71
	v_exp_f32_e32 v72, v72
	v_exp_f32_e32 v73, v73
	v_mul_f32_e32 v52, v52, v191
	v_mul_f32_e32 v53, v53, v191
	v_mul_f32_e32 v54, v54, v191
	v_mul_f32_e32 v55, v55, v191
	v_mul_f32_e32 v56, v56, v191
	v_mul_f32_e32 v57, v57, v191
	v_mul_f32_e32 v58, v58, v191
	v_mul_f32_e32 v59, v59, v191
	v_add_f32_e32 v64, 1.0, v64
	v_add_f32_e32 v65, 1.0, v65
	v_add_f32_e32 v68, 1.0, v68
	v_add_f32_e32 v69, 1.0, v69
	v_add_f32_e32 v70, 1.0, v70
	v_add_f32_e32 v71, 1.0, v71
	v_add_f32_e32 v72, 1.0, v72
	v_add_f32_e32 v73, 1.0, v73
	v_rcp_f32_e32 v64, v64
	v_rcp_f32_e32 v65, v65
	v_rcp_f32_e32 v68, v68
	v_rcp_f32_e32 v69, v69
	v_rcp_f32_e32 v70, v70
	v_rcp_f32_e32 v71, v71
	v_rcp_f32_e32 v72, v72
	v_rcp_f32_e32 v73, v73
	v_mul_f32_e32 v52, v52, v64
	v_mul_f32_e32 v53, v53, v65
	v_mul_f32_e32 v54, v54, v68
	v_mul_f32_e32 v55, v55, v69
	v_mul_f32_e32 v56, v56, v70
	v_mul_f32_e32 v57, v57, v71
	v_mul_f32_e32 v58, v58, v72
	v_mul_f32_e32 v59, v59, v73
	v_cvt_pk_bf16_f32 v48, v52, v53
	v_cvt_pk_bf16_f32 v49, v54, v55
	v_cvt_pk_bf16_f32 v50, v56, v57
	v_cvt_pk_bf16_f32 v51, v58, v59
	global_store_dwordx4 v[66:67], v[48:51], off
	s_nop 0
	s_waitcnt vmcnt(7)
; __device__ __forceinline__ unsigned cvtpk(float lo, float hi) { f32x2v_ v = {lo, hi}; bf16x2v_ b = __builtin_convertvector(v, bf16x2v_); return __builtin_bit_cast(unsigned, b); }
; __device__ __forceinline__ float row_rs(const float* ssp, int row) { const unsigned long long v = ((const unsigned long long*)ssp)[row];
;     return __builtin_amdgcn_rsqf((float)v * (1.0f / 4294967296.0f) * (1.0f / 1024.0f) + RMS_EPS); }
;     __device__ __forceinline__ void operator()(const f32x4 (&acc)[2][2][4][2], const Unit& u, int wr, int wc, int fr, int fq) const {
;     ...
;             for (int m = 0; m < 4; ++m) { const int row = row0 + ai * HALF + m * 16; const float rs = row_rs(ss, row);
;                 float hv[8];
; #pragma unroll
;                 for (int n = 0; n < 2; ++n)
; #pragma unroll
;                     for (int i = 0; i < 4; ++i) { const float g = acc[ai][0][m][n][i] * rs, uu = acc[ai][1][m][n][i] * rs;
;                         hv[n * 4 + i] = g * __builtin_amdgcn_rcpf(1.0f + __expf(-g)) * uu; }
;                 u32x4 w; w.x = cvtpk(hv[0], hv[1]); w.y = cvtpk(hv[2], hv[3]); w.z = cvtpk(hv[4], hv[5]); w.w = cvtpk(hv[6], hv[7]);
;                 *(u32x4*)(H + (size_t)row * ldh + col0) = w; }
	v_cvt_f32_u32_e32 v48, v193
	v_cvt_f32_u32_e32 v50, v192
	v_add_u32_e32 v49, 0x90, v144
	v_fmamk_f32 v48, v50, 0x2f800000, v48
	v_fmamk_f32 v48, v48, 0x3a800000, v158
	v_rsq_f32_e32 v48, v48
	v_mad_i64_i32 v[50:51], s[14:15], v49, s65, v[146:147]
	v_lshl_add_u64 v[50:51], v[50:51], 0, v[148:149]
	v_mul_f32_e32 v192, 0xbfb8aa3b, v48
	v_mul_f32_e32 v193, v48, v48
	v_mul_f32_e32 v48, v44, v192
	v_mul_f32_e32 v49, v45, v192
	v_mul_f32_e32 v52, v46, v192
	v_mul_f32_e32 v53, v47, v192
	v_mul_f32_e32 v54, v40, v192
	v_mul_f32_e32 v55, v41, v192
	v_mul_f32_e32 v56, v42, v192
	v_mul_f32_e32 v57, v43, v192
	v_mul_f32_e32 v36, v36, v44
	v_mul_f32_e32 v37, v37, v45
	v_mul_f32_e32 v38, v38, v46
	v_mul_f32_e32 v39, v39, v47
	v_mul_f32_e32 v40, v32, v40
	v_mul_f32_e32 v41, v33, v41
	v_mul_f32_e32 v42, v34, v42
	v_mul_f32_e32 v43, v35, v43
	v_exp_f32_e32 v48, v48
	v_exp_f32_e32 v49, v49
	v_exp_f32_e32 v52, v52
	v_exp_f32_e32 v53, v53
	v_exp_f32_e32 v54, v54
	v_exp_f32_e32 v55, v55
	v_exp_f32_e32 v56, v56
	v_exp_f32_e32 v57, v57
	v_mul_f32_e32 v36, v36, v193
	v_mul_f32_e32 v37, v37, v193
	v_mul_f32_e32 v38, v38, v193
	v_mul_f32_e32 v39, v39, v193
	v_mul_f32_e32 v40, v40, v193
	v_mul_f32_e32 v41, v41, v193
	v_mul_f32_e32 v42, v42, v193
	v_mul_f32_e32 v43, v43, v193
	v_add_f32_e32 v48, 1.0, v48
	v_add_f32_e32 v49, 1.0, v49
	v_add_f32_e32 v52, 1.0, v52
	v_add_f32_e32 v53, 1.0, v53
	v_add_f32_e32 v54, 1.0, v54
	v_add_f32_e32 v55, 1.0, v55
	v_add_f32_e32 v56, 1.0, v56
	v_add_f32_e32 v57, 1.0, v57
	v_rcp_f32_e32 v48, v48
	v_rcp_f32_e32 v49, v49
	v_rcp_f32_e32 v52, v52
	v_rcp_f32_e32 v53, v53
	v_rcp_f32_e32 v54, v54
	v_rcp_f32_e32 v55, v55
	v_rcp_f32_e32 v56, v56
	v_rcp_f32_e32 v57, v57
	v_mul_f32_e32 v36, v36, v48
	v_mul_f32_e32 v37, v37, v49
	v_mul_f32_e32 v38, v38, v52
	v_mul_f32_e32 v39, v39, v53
	v_mul_f32_e32 v40, v40, v54
	v_mul_f32_e32 v41, v41, v55
	v_mul_f32_e32 v42, v42, v56
	v_mul_f32_e32 v43, v43, v57
	v_cvt_pk_bf16_f32 v32, v36, v37
	v_cvt_pk_bf16_f32 v33, v38, v39
	v_cvt_pk_bf16_f32 v34, v40, v41
	v_cvt_pk_bf16_f32 v35, v42, v43
	global_store_dwordx4 v[50:51], v[32:35], off
	s_nop 0
	s_waitcnt vmcnt(7)
	v_cvt_f32_u32_e32 v32, v195
	v_cvt_f32_u32_e32 v34, v194
	v_add_u32_e32 v33, 0xa0, v144
	v_fmamk_f32 v32, v34, 0x2f800000, v32
	v_fmamk_f32 v32, v32, 0x3a800000, v158
	v_rsq_f32_e32 v32, v32
	v_mad_i64_i32 v[34:35], s[14:15], v33, s65, v[146:147]
	v_lshl_add_u64 v[34:35], v[34:35], 0, v[148:149]
	v_mul_f32_e32 v194, 0xbfb8aa3b, v32
	v_mul_f32_e32 v195, v32, v32
	v_mul_f32_e32 v32, v28, v194
	v_mul_f32_e32 v33, v29, v194
	v_mul_f32_e32 v36, v30, v194
	v_mul_f32_e32 v37, v31, v194
	v_mul_f32_e32 v38, v24, v194
	v_mul_f32_e32 v39, v25, v194
	v_mul_f32_e32 v40, v26, v194
	v_mul_f32_e32 v41, v27, v194
	v_mul_f32_e32 v20, v20, v28
	v_mul_f32_e32 v21, v21, v29
	v_mul_f32_e32 v22, v22, v30
	v_mul_f32_e32 v23, v23, v31
	v_mul_f32_e32 v24, v16, v24
	v_mul_f32_e32 v25, v17, v25
	v_mul_f32_e32 v26, v18, v26
	v_mul_f32_e32 v27, v19, v27
	v_exp_f32_e32 v32, v32
	v_exp_f32_e32 v33, v33
	v_exp_f32_e32 v36, v36
	v_exp_f32_e32 v37, v37
	v_exp_f32_e32 v38, v38
	v_exp_f32_e32 v39, v39
	v_exp_f32_e32 v40, v40
	v_exp_f32_e32 v41, v41
	v_mul_f32_e32 v20, v20, v195
	v_mul_f32_e32 v21, v21, v195
	v_mul_f32_e32 v22, v22, v195
	v_mul_f32_e32 v23, v23, v195
	v_mul_f32_e32 v24, v24, v195
	v_mul_f32_e32 v25, v25, v195
	v_mul_f32_e32 v26, v26, v195
	v_mul_f32_e32 v27, v27, v195
	v_add_f32_e32 v32, 1.0, v32
	v_add_f32_e32 v33, 1.0, v33
	v_add_f32_e32 v36, 1.0, v36
	v_add_f32_e32 v37, 1.0, v37
	v_add_f32_e32 v38, 1.0, v38
	v_add_f32_e32 v39, 1.0, v39
	v_add_f32_e32 v40, 1.0, v40
	v_add_f32_e32 v41, 1.0, v41
	v_rcp_f32_e32 v32, v32
	v_rcp_f32_e32 v33, v33
	v_rcp_f32_e32 v36, v36
	v_rcp_f32_e32 v37, v37
	v_rcp_f32_e32 v38, v38
	v_rcp_f32_e32 v39, v39
	v_rcp_f32_e32 v40, v40
	v_rcp_f32_e32 v41, v41
	v_mul_f32_e32 v20, v20, v32
	v_mul_f32_e32 v21, v21, v33
	v_mul_f32_e32 v22, v22, v36
	v_mul_f32_e32 v23, v23, v37
	v_mul_f32_e32 v24, v24, v38
	v_mul_f32_e32 v25, v25, v39
	v_mul_f32_e32 v26, v26, v40
	v_mul_f32_e32 v27, v27, v41
	v_cvt_pk_bf16_f32 v16, v20, v21
	v_cvt_pk_bf16_f32 v17, v22, v23
	v_cvt_pk_bf16_f32 v18, v24, v25
	v_cvt_pk_bf16_f32 v19, v26, v27
	global_store_dwordx4 v[34:35], v[16:19], off
	s_nop 0
	s_waitcnt vmcnt(7)
	v_cvt_f32_u32_e32 v16, v197
	v_cvt_f32_u32_e32 v18, v196
	v_add_u32_e32 v17, 0xb0, v144
	v_fmamk_f32 v16, v18, 0x2f800000, v16
	v_fmamk_f32 v16, v16, 0x3a800000, v158
	v_rsq_f32_e32 v16, v16
	v_mad_i64_i32 v[18:19], s[14:15], v17, s65, v[146:147]
	v_lshl_add_u64 v[18:19], v[18:19], 0, v[148:149]
	v_mul_f32_e32 v196, 0xbfb8aa3b, v16
	v_mul_f32_e32 v197, v16, v16
	v_mul_f32_e32 v16, v12, v196
	v_mul_f32_e32 v17, v13, v196
	v_mul_f32_e32 v20, v14, v196
	v_mul_f32_e32 v21, v15, v196
	v_mul_f32_e32 v22, v8, v196
	v_mul_f32_e32 v23, v9, v196
	v_mul_f32_e32 v24, v10, v196
	v_mul_f32_e32 v25, v11, v196
	v_mul_f32_e32 v4, v4, v12
	v_mul_f32_e32 v5, v5, v13
	v_mul_f32_e32 v6, v6, v14
	v_mul_f32_e32 v7, v7, v15
	v_mul_f32_e32 v8, v0, v8
	v_mul_f32_e32 v9, v1, v9
	v_mul_f32_e32 v10, v2, v10
	v_mul_f32_e32 v11, v3, v11
	v_exp_f32_e32 v16, v16
	v_exp_f32_e32 v17, v17
	v_exp_f32_e32 v20, v20
	v_exp_f32_e32 v21, v21
	v_exp_f32_e32 v22, v22
	v_exp_f32_e32 v23, v23
	v_exp_f32_e32 v24, v24
	v_exp_f32_e32 v25, v25
	v_mul_f32_e32 v4, v4, v197
	v_mul_f32_e32 v5, v5, v197
	v_mul_f32_e32 v6, v6, v197
	v_mul_f32_e32 v7, v7, v197
	v_mul_f32_e32 v8, v8, v197
	v_mul_f32_e32 v9, v9, v197
	v_mul_f32_e32 v10, v10, v197
	v_mul_f32_e32 v11, v11, v197
	v_add_f32_e32 v16, 1.0, v16
	v_add_f32_e32 v17, 1.0, v17
	v_add_f32_e32 v20, 1.0, v20
	v_add_f32_e32 v21, 1.0, v21
	v_add_f32_e32 v22, 1.0, v22
	v_add_f32_e32 v23, 1.0, v23
	v_add_f32_e32 v24, 1.0, v24
	v_add_f32_e32 v25, 1.0, v25
	v_rcp_f32_e32 v16, v16
	v_rcp_f32_e32 v17, v17
	v_rcp_f32_e32 v20, v20
	v_rcp_f32_e32 v21, v21
	v_rcp_f32_e32 v22, v22
	v_rcp_f32_e32 v23, v23
	v_rcp_f32_e32 v24, v24
	v_rcp_f32_e32 v25, v25
	v_mul_f32_e32 v4, v4, v16
	v_mul_f32_e32 v5, v5, v17
	v_mul_f32_e32 v6, v6, v20
	v_mul_f32_e32 v7, v7, v21
	v_mul_f32_e32 v8, v8, v22
	v_mul_f32_e32 v9, v9, v23
	v_mul_f32_e32 v10, v10, v24
	v_mul_f32_e32 v11, v11, v25
	v_cvt_pk_bf16_f32 v0, v4, v5
	v_cvt_pk_bf16_f32 v1, v6, v7
	v_cvt_pk_bf16_f32 v2, v8, v9
	v_cvt_pk_bf16_f32 v3, v10, v11
	global_store_dwordx4 v[18:19], v[0:3], off
	s_cbranch_vccnz .LBB0_187
	s_andn2_b64 vcc, exec, s[8:9]
	s_cbranch_vccnz .LBB0_186
	s_barrier
	s_branch .LBB0_186

; __device__ __forceinline__ unsigned cvtpk(float lo, float hi) { f32x2v_ v = {lo, hi}; bf16x2v_ b = __builtin_convertvector(v, bf16x2v_); return __builtin_bit_cast(unsigned, b); }
; __device__ __forceinline__ float row_rs(const float* ssp, int row) { const unsigned long long v = ((const unsigned long long*)ssp)[row];
;     return __builtin_amdgcn_rsqf((float)v * (1.0f / 4294967296.0f) * (1.0f / 1024.0f) + RMS_EPS); }
;     __device__ __forceinline__ void operator()(const f32x4 (&acc)[2][2][4][2], const Unit& u, int wr, int wc, int fr, int fq) const {
;     ...
;             for (int m = 0; m < 4; ++m) { const int row = row0 + ai * HALF + m * 16; const float rs = row_rs(ss, row);
;                 float hv[8];
; #pragma unroll
;                 for (int n = 0; n < 2; ++n)
; #pragma unroll
;                     for (int i = 0; i < 4; ++i) { const float g = acc[ai][0][m][n][i] * rs, uu = acc[ai][1][m][n][i] * rs;
;                         hv[n * 4 + i] = g * __builtin_amdgcn_rcpf(1.0f + __expf(-g)) * uu; }
;                 u32x4 w; w.x = cvtpk(hv[0], hv[1]); w.y = cvtpk(hv[2], hv[3]); w.z = cvtpk(hv[4], hv[5]); w.w = cvtpk(hv[6], hv[7]);
;                 *(u32x4*)(H + (size_t)row * ldh + col0) = w; }
.LBB0_960:
	v_lshl_or_b32 v160, s74, 7, v154
	v_ashrrev_i32_e32 v161, 31, v160
	v_or_b32_e32 v164, 16, v144
	v_ashrrev_i32_e32 v165, 31, v164
	v_lshl_add_u64 v[166:167], v[164:165], 3, s[0:1]
	v_mov_b64_e32 v[146:147], s[20:21]
	v_mad_i64_i32 v[162:163], s[54:55], v144, s67, v[146:147]
	s_andn2_b64 vcc, exec, s[10:11]
	s_mov_b64 s[10:11], -1
	s_waitcnt vmcnt(7)
	v_cvt_f32_u32_e32 v159, v183
	v_cvt_f32_u32_e32 v145, v182
	v_lshlrev_b64 v[148:149], 1, v[160:161]
	v_lshl_add_u64 v[162:163], v[162:163], 0, v[148:149]
	v_fmamk_f32 v145, v145, 0x2f800000, v159
	v_fmamk_f32 v145, v145, 0x3a800000, v158
	v_rsq_f32_e32 v160, v145
	s_nop 0
	v_mul_f32_e32 v182, 0xbfb8aa3b, v160
	v_mul_f32_e32 v183, v160, v160
	v_mul_f32_e32 v160, v124, v182
	v_mul_f32_e32 v161, v125, v182
	v_mul_f32_e32 v168, v126, v182
	v_mul_f32_e32 v169, v127, v182
	v_mul_f32_e32 v170, v120, v182
	v_mul_f32_e32 v171, v121, v182
	v_mul_f32_e32 v172, v122, v182
	v_mul_f32_e32 v173, v123, v182
	v_mul_f32_e32 v116, v116, v124
	v_mul_f32_e32 v117, v117, v125
	v_mul_f32_e32 v118, v118, v126
	v_mul_f32_e32 v119, v119, v127
	v_mul_f32_e32 v120, v112, v120
	v_mul_f32_e32 v121, v113, v121
	v_mul_f32_e32 v122, v114, v122
	v_mul_f32_e32 v123, v115, v123
	v_exp_f32_e32 v160, v160
	v_exp_f32_e32 v161, v161
	v_exp_f32_e32 v168, v168
	v_exp_f32_e32 v169, v169
	v_exp_f32_e32 v170, v170
	v_exp_f32_e32 v171, v171
	v_exp_f32_e32 v172, v172
	v_exp_f32_e32 v173, v173
	v_mul_f32_e32 v116, v116, v183
	v_mul_f32_e32 v117, v117, v183
	v_mul_f32_e32 v118, v118, v183
	v_mul_f32_e32 v119, v119, v183
	v_mul_f32_e32 v120, v120, v183
	v_mul_f32_e32 v121, v121, v183
	v_mul_f32_e32 v122, v122, v183
	v_mul_f32_e32 v123, v123, v183
	v_add_f32_e32 v160, 1.0, v160
	v_add_f32_e32 v161, 1.0, v161
	v_add_f32_e32 v168, 1.0, v168
	v_add_f32_e32 v169, 1.0, v169
	v_add_f32_e32 v170, 1.0, v170
	v_add_f32_e32 v171, 1.0, v171
	v_add_f32_e32 v172, 1.0, v172
	v_add_f32_e32 v173, 1.0, v173
	v_rcp_f32_e32 v160, v160
	v_rcp_f32_e32 v161, v161
	v_rcp_f32_e32 v168, v168
	v_rcp_f32_e32 v169, v169
	v_rcp_f32_e32 v170, v170
	v_rcp_f32_e32 v171, v171
	v_rcp_f32_e32 v172, v172
	v_rcp_f32_e32 v173, v173
	v_mul_f32_e32 v116, v116, v160
	v_mul_f32_e32 v117, v117, v161
	v_mul_f32_e32 v118, v118, v168
	v_mul_f32_e32 v119, v119, v169
	v_mul_f32_e32 v120, v120, v170
	v_mul_f32_e32 v121, v121, v171
	v_mul_f32_e32 v122, v122, v172
	v_mul_f32_e32 v123, v123, v173
	v_cvt_pk_bf16_f32 v112, v116, v117
	v_cvt_pk_bf16_f32 v113, v118, v119
	v_cvt_pk_bf16_f32 v114, v120, v121
	v_cvt_pk_bf16_f32 v115, v122, v123
	global_store_dwordx4 v[162:163], v[112:115], off
	s_nop 0
	s_nop 0
	v_or_b32_e32 v114, 32, v144
	s_waitcnt vmcnt(7)
	v_cvt_f32_u32_e32 v116, v185
	v_cvt_f32_u32_e32 v115, v184
	v_mad_i64_i32 v[112:113], s[54:55], v164, s67, v[146:147]
	v_fmamk_f32 v115, v115, 0x2f800000, v116
	v_fmamk_f32 v115, v115, 0x3a800000, v158
	v_rsq_f32_e32 v116, v115
	v_ashrrev_i32_e32 v115, 31, v114
	v_lshl_add_u64 v[118:119], v[114:115], 3, s[0:1]
	v_lshl_add_u64 v[112:113], v[112:113], 0, v[148:149]
	v_mul_f32_e32 v184, 0xbfb8aa3b, v116
	v_mul_f32_e32 v185, v116, v116
	v_mul_f32_e32 v116, v108, v184
	v_mul_f32_e32 v117, v109, v184
	v_mul_f32_e32 v120, v110, v184
	v_mul_f32_e32 v121, v111, v184
	v_mul_f32_e32 v122, v104, v184
	v_mul_f32_e32 v123, v105, v184
	v_mul_f32_e32 v124, v106, v184
	v_mul_f32_e32 v125, v107, v184
	v_mul_f32_e32 v100, v100, v108
	v_mul_f32_e32 v101, v101, v109
	v_mul_f32_e32 v102, v102, v110
	v_mul_f32_e32 v103, v103, v111
	v_mul_f32_e32 v104, v96, v104
	v_mul_f32_e32 v105, v97, v105
	v_mul_f32_e32 v106, v98, v106
	v_mul_f32_e32 v107, v99, v107
	v_exp_f32_e32 v116, v116
	v_exp_f32_e32 v117, v117
	v_exp_f32_e32 v120, v120
	v_exp_f32_e32 v121, v121
	v_exp_f32_e32 v122, v122
	v_exp_f32_e32 v123, v123
	v_exp_f32_e32 v124, v124
	v_exp_f32_e32 v125, v125
	v_mul_f32_e32 v100, v100, v185
	v_mul_f32_e32 v101, v101, v185
	v_mul_f32_e32 v102, v102, v185
	v_mul_f32_e32 v103, v103, v185
	v_mul_f32_e32 v104, v104, v185
	v_mul_f32_e32 v105, v105, v185
	v_mul_f32_e32 v106, v106, v185
	v_mul_f32_e32 v107, v107, v185
	v_add_f32_e32 v116, 1.0, v116
	v_add_f32_e32 v117, 1.0, v117
	v_add_f32_e32 v120, 1.0, v120
	v_add_f32_e32 v121, 1.0, v121
	v_add_f32_e32 v122, 1.0, v122
	v_add_f32_e32 v123, 1.0, v123
	v_add_f32_e32 v124, 1.0, v124
	v_add_f32_e32 v125, 1.0, v125
	v_rcp_f32_e32 v116, v116
	v_rcp_f32_e32 v117, v117
	v_rcp_f32_e32 v120, v120
	v_rcp_f32_e32 v121, v121
	v_rcp_f32_e32 v122, v122
	v_rcp_f32_e32 v123, v123
	v_rcp_f32_e32 v124, v124
	v_rcp_f32_e32 v125, v125
	v_mul_f32_e32 v100, v100, v116
	v_mul_f32_e32 v101, v101, v117
	v_mul_f32_e32 v102, v102, v120
	v_mul_f32_e32 v103, v103, v121
	v_mul_f32_e32 v104, v104, v122
	v_mul_f32_e32 v105, v105, v123
	v_mul_f32_e32 v106, v106, v124
	v_mul_f32_e32 v107, v107, v125
	v_cvt_pk_bf16_f32 v96, v100, v101
	v_cvt_pk_bf16_f32 v97, v102, v103
	v_cvt_pk_bf16_f32 v98, v104, v105
	v_cvt_pk_bf16_f32 v99, v106, v107
	global_store_dwordx4 v[112:113], v[96:99], off
	s_nop 0
	s_nop 0
	v_or_b32_e32 v98, 48, v144
	s_waitcnt vmcnt(7)
; __device__ __forceinline__ unsigned cvtpk(float lo, float hi) { f32x2v_ v = {lo, hi}; bf16x2v_ b = __builtin_convertvector(v, bf16x2v_); return __builtin_bit_cast(unsigned, b); }
; __device__ __forceinline__ float row_rs(const float* ssp, int row) { const unsigned long long v = ((const unsigned long long*)ssp)[row];
;     return __builtin_amdgcn_rsqf((float)v * (1.0f / 4294967296.0f) * (1.0f / 1024.0f) + RMS_EPS); }
;     __device__ __forceinline__ void operator()(const f32x4 (&acc)[2][2][4][2], const Unit& u, int wr, int wc, int fr, int fq) const {
;     ...
;             for (int m = 0; m < 4; ++m) { const int row = row0 + ai * HALF + m * 16; const float rs = row_rs(ss, row);
;                 float hv[8];
; #pragma unroll
;                 for (int n = 0; n < 2; ++n)
; #pragma unroll
;                     for (int i = 0; i < 4; ++i) { const float g = acc[ai][0][m][n][i] * rs, uu = acc[ai][1][m][n][i] * rs;
;                         hv[n * 4 + i] = g * __builtin_amdgcn_rcpf(1.0f + __expf(-g)) * uu; }
;                 u32x4 w; w.x = cvtpk(hv[0], hv[1]); w.y = cvtpk(hv[2], hv[3]); w.z = cvtpk(hv[4], hv[5]); w.w = cvtpk(hv[6], hv[7]);
;                 *(u32x4*)(H + (size_t)row * ldh + col0) = w; }
	v_cvt_f32_u32_e32 v100, v187
	v_cvt_f32_u32_e32 v99, v186
	v_mad_i64_i32 v[96:97], s[54:55], v114, s67, v[146:147]
	v_fmamk_f32 v99, v99, 0x2f800000, v100
	v_fmamk_f32 v99, v99, 0x3a800000, v158
	v_rsq_f32_e32 v100, v99
	v_ashrrev_i32_e32 v99, 31, v98
	v_lshl_add_u64 v[102:103], v[98:99], 3, s[0:1]
	v_lshl_add_u64 v[96:97], v[96:97], 0, v[148:149]
	v_mul_f32_e32 v186, 0xbfb8aa3b, v100
	v_mul_f32_e32 v187, v100, v100
	v_mul_f32_e32 v100, v92, v186
	v_mul_f32_e32 v101, v93, v186
	v_mul_f32_e32 v104, v94, v186
	v_mul_f32_e32 v105, v95, v186
	v_mul_f32_e32 v106, v88, v186
	v_mul_f32_e32 v107, v89, v186
	v_mul_f32_e32 v108, v90, v186
	v_mul_f32_e32 v109, v91, v186
	v_mul_f32_e32 v84, v84, v92
	v_mul_f32_e32 v85, v85, v93
	v_mul_f32_e32 v86, v86, v94
	v_mul_f32_e32 v87, v87, v95
	v_mul_f32_e32 v88, v80, v88
	v_mul_f32_e32 v89, v81, v89
	v_mul_f32_e32 v90, v82, v90
	v_mul_f32_e32 v91, v83, v91
	v_exp_f32_e32 v100, v100
	v_exp_f32_e32 v101, v101
	v_exp_f32_e32 v104, v104
	v_exp_f32_e32 v105, v105
	v_exp_f32_e32 v106, v106
	v_exp_f32_e32 v107, v107
	v_exp_f32_e32 v108, v108
	v_exp_f32_e32 v109, v109
	v_mul_f32_e32 v84, v84, v187
	v_mul_f32_e32 v85, v85, v187
	v_mul_f32_e32 v86, v86, v187
	v_mul_f32_e32 v87, v87, v187
	v_mul_f32_e32 v88, v88, v187
	v_mul_f32_e32 v89, v89, v187
	v_mul_f32_e32 v90, v90, v187
	v_mul_f32_e32 v91, v91, v187
	v_add_f32_e32 v100, 1.0, v100
	v_add_f32_e32 v101, 1.0, v101
	v_add_f32_e32 v104, 1.0, v104
	v_add_f32_e32 v105, 1.0, v105
	v_add_f32_e32 v106, 1.0, v106
	v_add_f32_e32 v107, 1.0, v107
	v_add_f32_e32 v108, 1.0, v108
	v_add_f32_e32 v109, 1.0, v109
	v_rcp_f32_e32 v100, v100
	v_rcp_f32_e32 v101, v101
	v_rcp_f32_e32 v104, v104
	v_rcp_f32_e32 v105, v105
	v_rcp_f32_e32 v106, v106
	v_rcp_f32_e32 v107, v107
	v_rcp_f32_e32 v108, v108
	v_rcp_f32_e32 v109, v109
	v_mul_f32_e32 v84, v84, v100
	v_mul_f32_e32 v85, v85, v101
	v_mul_f32_e32 v86, v86, v104
	v_mul_f32_e32 v87, v87, v105
	v_mul_f32_e32 v88, v88, v106
	v_mul_f32_e32 v89, v89, v107
	v_mul_f32_e32 v90, v90, v108
	v_mul_f32_e32 v91, v91, v109
	v_cvt_pk_bf16_f32 v80, v84, v85
	v_cvt_pk_bf16_f32 v81, v86, v87
	v_cvt_pk_bf16_f32 v82, v88, v89
	v_cvt_pk_bf16_f32 v83, v90, v91
	global_store_dwordx4 v[96:97], v[80:83], off
	s_nop 0
	s_waitcnt vmcnt(7)
	v_cvt_f32_u32_e32 v80, v189
	v_cvt_f32_u32_e32 v81, v188
	v_mad_i64_i32 v[82:83], s[54:55], v98, s67, v[146:147]
	v_fmamk_f32 v80, v81, 0x2f800000, v80
	v_fmamk_f32 v80, v80, 0x3a800000, v158
	v_rsq_f32_e32 v80, v80
	v_lshl_add_u64 v[82:83], v[82:83], 0, v[148:149]
	v_mul_f32_e32 v188, 0xbfb8aa3b, v80
	v_mul_f32_e32 v189, v80, v80
	v_mul_f32_e32 v80, v76, v188
	v_mul_f32_e32 v81, v77, v188
	v_mul_f32_e32 v84, v78, v188
	v_mul_f32_e32 v85, v79, v188
	v_mul_f32_e32 v86, v72, v188
	v_mul_f32_e32 v87, v73, v188
	v_mul_f32_e32 v88, v74, v188
	v_mul_f32_e32 v89, v75, v188
	v_mul_f32_e32 v68, v68, v76
	v_mul_f32_e32 v69, v69, v77
	v_mul_f32_e32 v70, v70, v78
	v_mul_f32_e32 v71, v71, v79
	v_mul_f32_e32 v72, v64, v72
	v_mul_f32_e32 v73, v65, v73
	v_mul_f32_e32 v74, v66, v74
	v_mul_f32_e32 v75, v67, v75
	v_exp_f32_e32 v80, v80
	v_exp_f32_e32 v81, v81
	v_exp_f32_e32 v84, v84
	v_exp_f32_e32 v85, v85
	v_exp_f32_e32 v86, v86
	v_exp_f32_e32 v87, v87
	v_exp_f32_e32 v88, v88
	v_exp_f32_e32 v89, v89
	v_mul_f32_e32 v68, v68, v189
	v_mul_f32_e32 v69, v69, v189
	v_mul_f32_e32 v70, v70, v189
	v_mul_f32_e32 v71, v71, v189
	v_mul_f32_e32 v72, v72, v189
	v_mul_f32_e32 v73, v73, v189
	v_mul_f32_e32 v74, v74, v189
	v_mul_f32_e32 v75, v75, v189
	v_add_f32_e32 v80, 1.0, v80
	v_add_f32_e32 v81, 1.0, v81
	v_add_f32_e32 v84, 1.0, v84
	v_add_f32_e32 v85, 1.0, v85
	v_add_f32_e32 v86, 1.0, v86
	v_add_f32_e32 v87, 1.0, v87
	v_add_f32_e32 v88, 1.0, v88
	v_add_f32_e32 v89, 1.0, v89
	v_rcp_f32_e32 v80, v80
	v_rcp_f32_e32 v81, v81
	v_rcp_f32_e32 v84, v84
	v_rcp_f32_e32 v85, v85
	v_rcp_f32_e32 v86, v86
	v_rcp_f32_e32 v87, v87
	v_rcp_f32_e32 v88, v88
	v_rcp_f32_e32 v89, v89
	v_mul_f32_e32 v68, v68, v80
	v_mul_f32_e32 v69, v69, v81
	v_mul_f32_e32 v70, v70, v84
	v_mul_f32_e32 v71, v71, v85
	v_mul_f32_e32 v72, v72, v86
	v_mul_f32_e32 v73, v73, v87
	v_mul_f32_e32 v74, v74, v88
	v_mul_f32_e32 v75, v75, v89
	v_cvt_pk_bf16_f32 v64, v68, v69
	v_cvt_pk_bf16_f32 v65, v70, v71
	v_cvt_pk_bf16_f32 v66, v72, v73
	v_cvt_pk_bf16_f32 v67, v74, v75
	global_store_dwordx4 v[82:83], v[64:67], off
	s_nop 0
	s_waitcnt vmcnt(7)
	v_cvt_f32_u32_e32 v64, v191
	v_cvt_f32_u32_e32 v66, v190
	v_add_u32_e32 v65, 0x80, v144
	v_fmamk_f32 v64, v66, 0x2f800000, v64
	v_fmamk_f32 v64, v64, 0x3a800000, v158
	v_rsq_f32_e32 v64, v64
	v_mad_i64_i32 v[66:67], s[54:55], v65, s67, v[146:147]
	v_lshl_add_u64 v[66:67], v[66:67], 0, v[148:149]
	v_mul_f32_e32 v190, 0xbfb8aa3b, v64
	v_mul_f32_e32 v191, v64, v64
	v_mul_f32_e32 v64, v60, v190
	v_mul_f32_e32 v65, v61, v190
	v_mul_f32_e32 v68, v62, v190
	v_mul_f32_e32 v69, v63, v190
	v_mul_f32_e32 v70, v56, v190
	v_mul_f32_e32 v71, v57, v190
	v_mul_f32_e32 v72, v58, v190
	v_mul_f32_e32 v73, v59, v190
	v_mul_f32_e32 v52, v52, v60
	v_mul_f32_e32 v53, v53, v61
	v_mul_f32_e32 v54, v54, v62
	v_mul_f32_e32 v55, v55, v63
	v_mul_f32_e32 v56, v48, v56
	v_mul_f32_e32 v57, v49, v57
	v_mul_f32_e32 v58, v50, v58
	v_mul_f32_e32 v59, v51, v59
	v_exp_f32_e32 v64, v64
	v_exp_f32_e32 v65, v65
	v_exp_f32_e32 v68, v68
	v_exp_f32_e32 v69, v69
	v_exp_f32_e32 v70, v70
	v_exp_f32_e32 v71, v71
	v_exp_f32_e32 v72, v72
	v_exp_f32_e32 v73, v73
	v_mul_f32_e32 v52, v52, v191
	v_mul_f32_e32 v53, v53, v191
	v_mul_f32_e32 v54, v54, v191
	v_mul_f32_e32 v55, v55, v191
	v_mul_f32_e32 v56, v56, v191
	v_mul_f32_e32 v57, v57, v191
	v_mul_f32_e32 v58, v58, v191
	v_mul_f32_e32 v59, v59, v191
	v_add_f32_e32 v64, 1.0, v64
	v_add_f32_e32 v65, 1.0, v65
	v_add_f32_e32 v68, 1.0, v68
	v_add_f32_e32 v69, 1.0, v69
	v_add_f32_e32 v70, 1.0, v70
	v_add_f32_e32 v71, 1.0, v71
	v_add_f32_e32 v72, 1.0, v72
	v_add_f32_e32 v73, 1.0, v73
	v_rcp_f32_e32 v64, v64
	v_rcp_f32_e32 v65, v65
	v_rcp_f32_e32 v68, v68
	v_rcp_f32_e32 v69, v69
	v_rcp_f32_e32 v70, v70
	v_rcp_f32_e32 v71, v71
	v_rcp_f32_e32 v72, v72
	v_rcp_f32_e32 v73, v73
	v_mul_f32_e32 v52, v52, v64
	v_mul_f32_e32 v53, v53, v65
	v_mul_f32_e32 v54, v54, v68
	v_mul_f32_e32 v55, v55, v69
	v_mul_f32_e32 v56, v56, v70
	v_mul_f32_e32 v57, v57, v71
	v_mul_f32_e32 v58, v58, v72
	v_mul_f32_e32 v59, v59, v73
	v_cvt_pk_bf16_f32 v48, v52, v53
	v_cvt_pk_bf16_f32 v49, v54, v55
	v_cvt_pk_bf16_f32 v50, v56, v57
	v_cvt_pk_bf16_f32 v51, v58, v59
	global_store_dwordx4 v[66:67], v[48:51], off
	s_nop 0
	s_waitcnt vmcnt(7)
; __device__ __forceinline__ unsigned cvtpk(float lo, float hi) { f32x2v_ v = {lo, hi}; bf16x2v_ b = __builtin_convertvector(v, bf16x2v_); return __builtin_bit_cast(unsigned, b); }
; __device__ __forceinline__ float row_rs(const float* ssp, int row) { const unsigned long long v = ((const unsigned long long*)ssp)[row];
;     return __builtin_amdgcn_rsqf((float)v * (1.0f / 4294967296.0f) * (1.0f / 1024.0f) + RMS_EPS); }
;     __device__ __forceinline__ void operator()(const f32x4 (&acc)[2][2][4][2], const Unit& u, int wr, int wc, int fr, int fq) const {
;     ...
;             for (int m = 0; m < 4; ++m) { const int row = row0 + ai * HALF + m * 16; const float rs = row_rs(ss, row);
;                 float hv[8];
; #pragma unroll
;                 for (int n = 0; n < 2; ++n)
; #pragma unroll
;                     for (int i = 0; i < 4; ++i) { const float g = acc[ai][0][m][n][i] * rs, uu = acc[ai][1][m][n][i] * rs;
;                         hv[n * 4 + i] = g * __builtin_amdgcn_rcpf(1.0f + __expf(-g)) * uu; }
;                 u32x4 w; w.x = cvtpk(hv[0], hv[1]); w.y = cvtpk(hv[2], hv[3]); w.z = cvtpk(hv[4], hv[5]); w.w = cvtpk(hv[6], hv[7]);
;                 *(u32x4*)(H + (size_t)row * ldh + col0) = w; }
	v_cvt_f32_u32_e32 v48, v193
	v_cvt_f32_u32_e32 v50, v192
	v_add_u32_e32 v49, 0x90, v144
	v_fmamk_f32 v48, v50, 0x2f800000, v48
	v_fmamk_f32 v48, v48, 0x3a800000, v158
	v_rsq_f32_e32 v48, v48
	v_mad_i64_i32 v[50:51], s[54:55], v49, s67, v[146:147]
	v_lshl_add_u64 v[50:51], v[50:51], 0, v[148:149]
	v_mul_f32_e32 v192, 0xbfb8aa3b, v48
	v_mul_f32_e32 v193, v48, v48
	v_mul_f32_e32 v48, v44, v192
	v_mul_f32_e32 v49, v45, v192
	v_mul_f32_e32 v52, v46, v192
	v_mul_f32_e32 v53, v47, v192
	v_mul_f32_e32 v54, v40, v192
	v_mul_f32_e32 v55, v41, v192
	v_mul_f32_e32 v56, v42, v192
	v_mul_f32_e32 v57, v43, v192
	v_mul_f32_e32 v36, v36, v44
	v_mul_f32_e32 v37, v37, v45
	v_mul_f32_e32 v38, v38, v46
	v_mul_f32_e32 v39, v39, v47
	v_mul_f32_e32 v40, v32, v40
	v_mul_f32_e32 v41, v33, v41
	v_mul_f32_e32 v42, v34, v42
	v_mul_f32_e32 v43, v35, v43
	v_exp_f32_e32 v48, v48
	v_exp_f32_e32 v49, v49
	v_exp_f32_e32 v52, v52
	v_exp_f32_e32 v53, v53
	v_exp_f32_e32 v54, v54
	v_exp_f32_e32 v55, v55
	v_exp_f32_e32 v56, v56
	v_exp_f32_e32 v57, v57
	v_mul_f32_e32 v36, v36, v193
	v_mul_f32_e32 v37, v37, v193
	v_mul_f32_e32 v38, v38, v193
	v_mul_f32_e32 v39, v39, v193
	v_mul_f32_e32 v40, v40, v193
	v_mul_f32_e32 v41, v41, v193
	v_mul_f32_e32 v42, v42, v193
	v_mul_f32_e32 v43, v43, v193
	v_add_f32_e32 v48, 1.0, v48
	v_add_f32_e32 v49, 1.0, v49
	v_add_f32_e32 v52, 1.0, v52
	v_add_f32_e32 v53, 1.0, v53
	v_add_f32_e32 v54, 1.0, v54
	v_add_f32_e32 v55, 1.0, v55
	v_add_f32_e32 v56, 1.0, v56
	v_add_f32_e32 v57, 1.0, v57
	v_rcp_f32_e32 v48, v48
	v_rcp_f32_e32 v49, v49
	v_rcp_f32_e32 v52, v52
	v_rcp_f32_e32 v53, v53
	v_rcp_f32_e32 v54, v54
	v_rcp_f32_e32 v55, v55
	v_rcp_f32_e32 v56, v56
	v_rcp_f32_e32 v57, v57
	v_mul_f32_e32 v36, v36, v48
	v_mul_f32_e32 v37, v37, v49
	v_mul_f32_e32 v38, v38, v52
	v_mul_f32_e32 v39, v39, v53
	v_mul_f32_e32 v40, v40, v54
	v_mul_f32_e32 v41, v41, v55
	v_mul_f32_e32 v42, v42, v56
	v_mul_f32_e32 v43, v43, v57
	v_cvt_pk_bf16_f32 v32, v36, v37
	v_cvt_pk_bf16_f32 v33, v38, v39
	v_cvt_pk_bf16_f32 v34, v40, v41
	v_cvt_pk_bf16_f32 v35, v42, v43
	global_store_dwordx4 v[50:51], v[32:35], off
	s_nop 0
	s_waitcnt vmcnt(7)
	v_cvt_f32_u32_e32 v32, v195
	v_cvt_f32_u32_e32 v34, v194
	v_add_u32_e32 v33, 0xa0, v144
	v_fmamk_f32 v32, v34, 0x2f800000, v32
	v_fmamk_f32 v32, v32, 0x3a800000, v158
	v_rsq_f32_e32 v32, v32
	v_mad_i64_i32 v[34:35], s[54:55], v33, s67, v[146:147]
	v_lshl_add_u64 v[34:35], v[34:35], 0, v[148:149]
	v_mul_f32_e32 v194, 0xbfb8aa3b, v32
	v_mul_f32_e32 v195, v32, v32
	v_mul_f32_e32 v32, v28, v194
	v_mul_f32_e32 v33, v29, v194
	v_mul_f32_e32 v36, v30, v194
	v_mul_f32_e32 v37, v31, v194
	v_mul_f32_e32 v38, v24, v194
	v_mul_f32_e32 v39, v25, v194
	v_mul_f32_e32 v40, v26, v194
	v_mul_f32_e32 v41, v27, v194
	v_mul_f32_e32 v20, v20, v28
	v_mul_f32_e32 v21, v21, v29
	v_mul_f32_e32 v22, v22, v30
	v_mul_f32_e32 v23, v23, v31
	v_mul_f32_e32 v24, v16, v24
	v_mul_f32_e32 v25, v17, v25
	v_mul_f32_e32 v26, v18, v26
	v_mul_f32_e32 v27, v19, v27
	v_exp_f32_e32 v32, v32
	v_exp_f32_e32 v33, v33
	v_exp_f32_e32 v36, v36
	v_exp_f32_e32 v37, v37
	v_exp_f32_e32 v38, v38
	v_exp_f32_e32 v39, v39
	v_exp_f32_e32 v40, v40
	v_exp_f32_e32 v41, v41
	v_mul_f32_e32 v20, v20, v195
	v_mul_f32_e32 v21, v21, v195
	v_mul_f32_e32 v22, v22, v195
	v_mul_f32_e32 v23, v23, v195
	v_mul_f32_e32 v24, v24, v195
	v_mul_f32_e32 v25, v25, v195
	v_mul_f32_e32 v26, v26, v195
	v_mul_f32_e32 v27, v27, v195
	v_add_f32_e32 v32, 1.0, v32
	v_add_f32_e32 v33, 1.0, v33
	v_add_f32_e32 v36, 1.0, v36
	v_add_f32_e32 v37, 1.0, v37
	v_add_f32_e32 v38, 1.0, v38
	v_add_f32_e32 v39, 1.0, v39
	v_add_f32_e32 v40, 1.0, v40
	v_add_f32_e32 v41, 1.0, v41
	v_rcp_f32_e32 v32, v32
	v_rcp_f32_e32 v33, v33
	v_rcp_f32_e32 v36, v36
	v_rcp_f32_e32 v37, v37
	v_rcp_f32_e32 v38, v38
	v_rcp_f32_e32 v39, v39
	v_rcp_f32_e32 v40, v40
	v_rcp_f32_e32 v41, v41
	v_mul_f32_e32 v20, v20, v32
	v_mul_f32_e32 v21, v21, v33
	v_mul_f32_e32 v22, v22, v36
	v_mul_f32_e32 v23, v23, v37
	v_mul_f32_e32 v24, v24, v38
	v_mul_f32_e32 v25, v25, v39
	v_mul_f32_e32 v26, v26, v40
	v_mul_f32_e32 v27, v27, v41
	v_cvt_pk_bf16_f32 v16, v20, v21
	v_cvt_pk_bf16_f32 v17, v22, v23
	v_cvt_pk_bf16_f32 v18, v24, v25
	v_cvt_pk_bf16_f32 v19, v26, v27
	global_store_dwordx4 v[34:35], v[16:19], off
	s_nop 0
	s_waitcnt vmcnt(7)
	v_cvt_f32_u32_e32 v16, v197
	v_cvt_f32_u32_e32 v18, v196
	v_add_u32_e32 v17, 0xb0, v144
	v_fmamk_f32 v16, v18, 0x2f800000, v16
	v_fmamk_f32 v16, v16, 0x3a800000, v158
	v_rsq_f32_e32 v16, v16
	v_mad_i64_i32 v[18:19], s[54:55], v17, s67, v[146:147]
	v_lshl_add_u64 v[18:19], v[18:19], 0, v[148:149]
	v_mul_f32_e32 v196, 0xbfb8aa3b, v16
	v_mul_f32_e32 v197, v16, v16
	v_mul_f32_e32 v16, v12, v196
	v_mul_f32_e32 v17, v13, v196
	v_mul_f32_e32 v20, v14, v196
	v_mul_f32_e32 v21, v15, v196
	v_mul_f32_e32 v22, v8, v196
	v_mul_f32_e32 v23, v9, v196
	v_mul_f32_e32 v24, v10, v196
	v_mul_f32_e32 v25, v11, v196
	v_mul_f32_e32 v4, v4, v12
	v_mul_f32_e32 v5, v5, v13
	v_mul_f32_e32 v6, v6, v14
	v_mul_f32_e32 v7, v7, v15
	v_mul_f32_e32 v8, v0, v8
	v_mul_f32_e32 v9, v1, v9
	v_mul_f32_e32 v10, v2, v10
	v_mul_f32_e32 v11, v3, v11
	v_exp_f32_e32 v16, v16
	v_exp_f32_e32 v17, v17
	v_exp_f32_e32 v20, v20
	v_exp_f32_e32 v21, v21
	v_exp_f32_e32 v22, v22
	v_exp_f32_e32 v23, v23
	v_exp_f32_e32 v24, v24
	v_exp_f32_e32 v25, v25
	v_mul_f32_e32 v4, v4, v197
	v_mul_f32_e32 v5, v5, v197
	v_mul_f32_e32 v6, v6, v197
	v_mul_f32_e32 v7, v7, v197
	v_mul_f32_e32 v8, v8, v197
	v_mul_f32_e32 v9, v9, v197
	v_mul_f32_e32 v10, v10, v197
	v_mul_f32_e32 v11, v11, v197
	v_add_f32_e32 v16, 1.0, v16
	v_add_f32_e32 v17, 1.0, v17
	v_add_f32_e32 v20, 1.0, v20
	v_add_f32_e32 v21, 1.0, v21
	v_add_f32_e32 v22, 1.0, v22
	v_add_f32_e32 v23, 1.0, v23
	v_add_f32_e32 v24, 1.0, v24
	v_add_f32_e32 v25, 1.0, v25
	v_rcp_f32_e32 v16, v16
	v_rcp_f32_e32 v17, v17
	v_rcp_f32_e32 v20, v20
	v_rcp_f32_e32 v21, v21
	v_rcp_f32_e32 v22, v22
	v_rcp_f32_e32 v23, v23
	v_rcp_f32_e32 v24, v24
	v_rcp_f32_e32 v25, v25
	v_mul_f32_e32 v4, v4, v16
	v_mul_f32_e32 v5, v5, v17
	v_mul_f32_e32 v6, v6, v20
	v_mul_f32_e32 v7, v7, v21
	v_mul_f32_e32 v8, v8, v22
	v_mul_f32_e32 v9, v9, v23
	v_mul_f32_e32 v10, v10, v24
	v_mul_f32_e32 v11, v11, v25
	v_cvt_pk_bf16_f32 v0, v4, v5
	v_cvt_pk_bf16_f32 v1, v6, v7
	v_cvt_pk_bf16_f32 v2, v8, v9
	v_cvt_pk_bf16_f32 v3, v10, v11
	global_store_dwordx4 v[18:19], v[0:3], off
	s_cbranch_vccnz .LBB0_953
	s_andn2_b64 vcc, exec, s[12:13]
	s_cbranch_vccnz .LBB0_952
	s_barrier
	s_branch .LBB0_952

; __device__ __forceinline__ unsigned cvtpk(float lo, float hi) { f32x2v_ v = {lo, hi}; bf16x2v_ b = __builtin_convertvector(v, bf16x2v_); return __builtin_bit_cast(unsigned, b); }
; __device__ __forceinline__ float row_rs(const float* ssp, int row) { const unsigned long long v = ((const unsigned long long*)ssp)[row];
;     return __builtin_amdgcn_rsqf((float)v * (1.0f / 4294967296.0f) * (1.0f / 1024.0f) + RMS_EPS); }
;     __device__ __forceinline__ void operator()(const f32x4 (&acc)[2][2][4][2], const Unit& u, int wr, int wc, int fr, int fq) const {
;     ...
;             for (int m = 0; m < 4; ++m) { const int row = row0 + ai * HALF + m * 16; const float rs = row_rs(ss, row);
;                 float hv[8];
; #pragma unroll
;                 for (int n = 0; n < 2; ++n)
; #pragma unroll
;                     for (int i = 0; i < 4; ++i) { const float g = acc[ai][0][m][n][i] * rs, uu = acc[ai][1][m][n][i] * rs;
;                         hv[n * 4 + i] = g * __builtin_amdgcn_rcpf(1.0f + __expf(-g)) * uu; }
;                 u32x4 w; w.x = cvtpk(hv[0], hv[1]); w.y = cvtpk(hv[2], hv[3]); w.z = cvtpk(hv[4], hv[5]); w.w = cvtpk(hv[6], hv[7]);
;                 *(u32x4*)(H + (size_t)row * ldh + col0) = w; }
.LBB0_1122:
	v_lshl_or_b32 v160, s75, 7, v154
	v_ashrrev_i32_e32 v161, 31, v160
	v_or_b32_e32 v164, 16, v144
	v_ashrrev_i32_e32 v165, 31, v164
	v_lshl_add_u64 v[166:167], v[164:165], 3, s[36:37]
	v_mov_b64_e32 v[146:147], s[20:21]
	v_mad_i64_i32 v[162:163], s[54:55], v144, s74, v[146:147]
	s_andn2_b64 vcc, exec, s[10:11]
	s_mov_b64 s[10:11], -1
	s_waitcnt vmcnt(7)
	v_cvt_f32_u32_e32 v159, v183
	v_cvt_f32_u32_e32 v145, v182
	v_lshlrev_b64 v[148:149], 1, v[160:161]
	v_lshl_add_u64 v[162:163], v[162:163], 0, v[148:149]
	v_fmamk_f32 v145, v145, 0x2f800000, v159
	v_fmamk_f32 v145, v145, 0x3a800000, v158
	v_rsq_f32_e32 v160, v145
	s_nop 0
	v_mul_f32_e32 v182, 0xbfb8aa3b, v160
	v_mul_f32_e32 v183, v160, v160
	v_mul_f32_e32 v160, v124, v182
	v_mul_f32_e32 v161, v125, v182
	v_mul_f32_e32 v168, v126, v182
	v_mul_f32_e32 v169, v127, v182
	v_mul_f32_e32 v170, v120, v182
	v_mul_f32_e32 v171, v121, v182
	v_mul_f32_e32 v172, v122, v182
	v_mul_f32_e32 v173, v123, v182
	v_mul_f32_e32 v116, v116, v124
	v_mul_f32_e32 v117, v117, v125
	v_mul_f32_e32 v118, v118, v126
	v_mul_f32_e32 v119, v119, v127
	v_mul_f32_e32 v120, v112, v120
	v_mul_f32_e32 v121, v113, v121
	v_mul_f32_e32 v122, v114, v122
	v_mul_f32_e32 v123, v115, v123
	v_exp_f32_e32 v160, v160
	v_exp_f32_e32 v161, v161
	v_exp_f32_e32 v168, v168
	v_exp_f32_e32 v169, v169
	v_exp_f32_e32 v170, v170
	v_exp_f32_e32 v171, v171
	v_exp_f32_e32 v172, v172
	v_exp_f32_e32 v173, v173
	v_mul_f32_e32 v116, v116, v183
	v_mul_f32_e32 v117, v117, v183
	v_mul_f32_e32 v118, v118, v183
	v_mul_f32_e32 v119, v119, v183
	v_mul_f32_e32 v120, v120, v183
	v_mul_f32_e32 v121, v121, v183
	v_mul_f32_e32 v122, v122, v183
	v_mul_f32_e32 v123, v123, v183
	v_add_f32_e32 v160, 1.0, v160
	v_add_f32_e32 v161, 1.0, v161
	v_add_f32_e32 v168, 1.0, v168
	v_add_f32_e32 v169, 1.0, v169
	v_add_f32_e32 v170, 1.0, v170
	v_add_f32_e32 v171, 1.0, v171
	v_add_f32_e32 v172, 1.0, v172
	v_add_f32_e32 v173, 1.0, v173
	v_rcp_f32_e32 v160, v160
	v_rcp_f32_e32 v161, v161
	v_rcp_f32_e32 v168, v168
	v_rcp_f32_e32 v169, v169
	v_rcp_f32_e32 v170, v170
	v_rcp_f32_e32 v171, v171
	v_rcp_f32_e32 v172, v172
	v_rcp_f32_e32 v173, v173
	v_mul_f32_e32 v116, v116, v160
	v_mul_f32_e32 v117, v117, v161
	v_mul_f32_e32 v118, v118, v168
	v_mul_f32_e32 v119, v119, v169
	v_mul_f32_e32 v120, v120, v170
	v_mul_f32_e32 v121, v121, v171
	v_mul_f32_e32 v122, v122, v172
	v_mul_f32_e32 v123, v123, v173
	v_cvt_pk_bf16_f32 v112, v116, v117
	v_cvt_pk_bf16_f32 v113, v118, v119
	v_cvt_pk_bf16_f32 v114, v120, v121
	v_cvt_pk_bf16_f32 v115, v122, v123
	global_store_dwordx4 v[162:163], v[112:115], off
	s_nop 0
	s_nop 0
	v_or_b32_e32 v114, 32, v144
	s_waitcnt vmcnt(7)
	v_cvt_f32_u32_e32 v116, v185
	v_cvt_f32_u32_e32 v115, v184
	v_mad_i64_i32 v[112:113], s[54:55], v164, s74, v[146:147]
	v_fmamk_f32 v115, v115, 0x2f800000, v116
	v_fmamk_f32 v115, v115, 0x3a800000, v158
	v_rsq_f32_e32 v116, v115
	v_ashrrev_i32_e32 v115, 31, v114
	v_lshl_add_u64 v[118:119], v[114:115], 3, s[36:37]
	v_lshl_add_u64 v[112:113], v[112:113], 0, v[148:149]
	v_mul_f32_e32 v184, 0xbfb8aa3b, v116
	v_mul_f32_e32 v185, v116, v116
	v_mul_f32_e32 v116, v108, v184
	v_mul_f32_e32 v117, v109, v184
	v_mul_f32_e32 v120, v110, v184
	v_mul_f32_e32 v121, v111, v184
	v_mul_f32_e32 v122, v104, v184
	v_mul_f32_e32 v123, v105, v184
	v_mul_f32_e32 v124, v106, v184
	v_mul_f32_e32 v125, v107, v184
	v_mul_f32_e32 v100, v100, v108
	v_mul_f32_e32 v101, v101, v109
	v_mul_f32_e32 v102, v102, v110
	v_mul_f32_e32 v103, v103, v111
	v_mul_f32_e32 v104, v96, v104
	v_mul_f32_e32 v105, v97, v105
	v_mul_f32_e32 v106, v98, v106
	v_mul_f32_e32 v107, v99, v107
	v_exp_f32_e32 v116, v116
	v_exp_f32_e32 v117, v117
	v_exp_f32_e32 v120, v120
	v_exp_f32_e32 v121, v121
	v_exp_f32_e32 v122, v122
	v_exp_f32_e32 v123, v123
	v_exp_f32_e32 v124, v124
	v_exp_f32_e32 v125, v125
	v_mul_f32_e32 v100, v100, v185
	v_mul_f32_e32 v101, v101, v185
	v_mul_f32_e32 v102, v102, v185
	v_mul_f32_e32 v103, v103, v185
	v_mul_f32_e32 v104, v104, v185
	v_mul_f32_e32 v105, v105, v185
	v_mul_f32_e32 v106, v106, v185
	v_mul_f32_e32 v107, v107, v185
	v_add_f32_e32 v116, 1.0, v116
	v_add_f32_e32 v117, 1.0, v117
	v_add_f32_e32 v120, 1.0, v120
	v_add_f32_e32 v121, 1.0, v121
	v_add_f32_e32 v122, 1.0, v122
	v_add_f32_e32 v123, 1.0, v123
	v_add_f32_e32 v124, 1.0, v124
	v_add_f32_e32 v125, 1.0, v125
	v_rcp_f32_e32 v116, v116
	v_rcp_f32_e32 v117, v117
	v_rcp_f32_e32 v120, v120
	v_rcp_f32_e32 v121, v121
	v_rcp_f32_e32 v122, v122
	v_rcp_f32_e32 v123, v123
	v_rcp_f32_e32 v124, v124
	v_rcp_f32_e32 v125, v125
	v_mul_f32_e32 v100, v100, v116
	v_mul_f32_e32 v101, v101, v117
	v_mul_f32_e32 v102, v102, v120
	v_mul_f32_e32 v103, v103, v121
	v_mul_f32_e32 v104, v104, v122
	v_mul_f32_e32 v105, v105, v123
	v_mul_f32_e32 v106, v106, v124
	v_mul_f32_e32 v107, v107, v125
	v_cvt_pk_bf16_f32 v96, v100, v101
	v_cvt_pk_bf16_f32 v97, v102, v103
	v_cvt_pk_bf16_f32 v98, v104, v105
	v_cvt_pk_bf16_f32 v99, v106, v107
	global_store_dwordx4 v[112:113], v[96:99], off
	s_nop 0
	s_nop 0
	v_or_b32_e32 v98, 48, v144
	s_waitcnt vmcnt(7)
; __device__ __forceinline__ unsigned cvtpk(float lo, float hi) { f32x2v_ v = {lo, hi}; bf16x2v_ b = __builtin_convertvector(v, bf16x2v_); return __builtin_bit_cast(unsigned, b); }
; __device__ __forceinline__ float row_rs(const float* ssp, int row) { const unsigned long long v = ((const unsigned long long*)ssp)[row];
;     return __builtin_amdgcn_rsqf((float)v * (1.0f / 4294967296.0f) * (1.0f / 1024.0f) + RMS_EPS); }
;     __device__ __forceinline__ void operator()(const f32x4 (&acc)[2][2][4][2], const Unit& u, int wr, int wc, int fr, int fq) const {
;     ...
;             for (int m = 0; m < 4; ++m) { const int row = row0 + ai * HALF + m * 16; const float rs = row_rs(ss, row);
;                 float hv[8];
; #pragma unroll
;                 for (int n = 0; n < 2; ++n)
; #pragma unroll
;                     for (int i = 0; i < 4; ++i) { const float g = acc[ai][0][m][n][i] * rs, uu = acc[ai][1][m][n][i] * rs;
;                         hv[n * 4 + i] = g * __builtin_amdgcn_rcpf(1.0f + __expf(-g)) * uu; }
;                 u32x4 w; w.x = cvtpk(hv[0], hv[1]); w.y = cvtpk(hv[2], hv[3]); w.z = cvtpk(hv[4], hv[5]); w.w = cvtpk(hv[6], hv[7]);
;                 *(u32x4*)(H + (size_t)row * ldh + col0) = w; }
	v_cvt_f32_u32_e32 v100, v187
	v_cvt_f32_u32_e32 v99, v186
	v_mad_i64_i32 v[96:97], s[54:55], v114, s74, v[146:147]
	v_fmamk_f32 v99, v99, 0x2f800000, v100
	v_fmamk_f32 v99, v99, 0x3a800000, v158
	v_rsq_f32_e32 v100, v99
	v_ashrrev_i32_e32 v99, 31, v98
	v_lshl_add_u64 v[102:103], v[98:99], 3, s[36:37]
	v_lshl_add_u64 v[96:97], v[96:97], 0, v[148:149]
	v_mul_f32_e32 v186, 0xbfb8aa3b, v100
	v_mul_f32_e32 v187, v100, v100
	v_mul_f32_e32 v100, v92, v186
	v_mul_f32_e32 v101, v93, v186
	v_mul_f32_e32 v104, v94, v186
	v_mul_f32_e32 v105, v95, v186
	v_mul_f32_e32 v106, v88, v186
	v_mul_f32_e32 v107, v89, v186
	v_mul_f32_e32 v108, v90, v186
	v_mul_f32_e32 v109, v91, v186
	v_mul_f32_e32 v84, v84, v92
	v_mul_f32_e32 v85, v85, v93
	v_mul_f32_e32 v86, v86, v94
	v_mul_f32_e32 v87, v87, v95
	v_mul_f32_e32 v88, v80, v88
	v_mul_f32_e32 v89, v81, v89
	v_mul_f32_e32 v90, v82, v90
	v_mul_f32_e32 v91, v83, v91
	v_exp_f32_e32 v100, v100
	v_exp_f32_e32 v101, v101
	v_exp_f32_e32 v104, v104
	v_exp_f32_e32 v105, v105
	v_exp_f32_e32 v106, v106
	v_exp_f32_e32 v107, v107
	v_exp_f32_e32 v108, v108
	v_exp_f32_e32 v109, v109
	v_mul_f32_e32 v84, v84, v187
	v_mul_f32_e32 v85, v85, v187
	v_mul_f32_e32 v86, v86, v187
	v_mul_f32_e32 v87, v87, v187
	v_mul_f32_e32 v88, v88, v187
	v_mul_f32_e32 v89, v89, v187
	v_mul_f32_e32 v90, v90, v187
	v_mul_f32_e32 v91, v91, v187
	v_add_f32_e32 v100, 1.0, v100
	v_add_f32_e32 v101, 1.0, v101
	v_add_f32_e32 v104, 1.0, v104
	v_add_f32_e32 v105, 1.0, v105
	v_add_f32_e32 v106, 1.0, v106
	v_add_f32_e32 v107, 1.0, v107
	v_add_f32_e32 v108, 1.0, v108
	v_add_f32_e32 v109, 1.0, v109
	v_rcp_f32_e32 v100, v100
	v_rcp_f32_e32 v101, v101
	v_rcp_f32_e32 v104, v104
	v_rcp_f32_e32 v105, v105
	v_rcp_f32_e32 v106, v106
	v_rcp_f32_e32 v107, v107
	v_rcp_f32_e32 v108, v108
	v_rcp_f32_e32 v109, v109
	v_mul_f32_e32 v84, v84, v100
	v_mul_f32_e32 v85, v85, v101
	v_mul_f32_e32 v86, v86, v104
	v_mul_f32_e32 v87, v87, v105
	v_mul_f32_e32 v88, v88, v106
	v_mul_f32_e32 v89, v89, v107
	v_mul_f32_e32 v90, v90, v108
	v_mul_f32_e32 v91, v91, v109
	v_cvt_pk_bf16_f32 v80, v84, v85
	v_cvt_pk_bf16_f32 v81, v86, v87
	v_cvt_pk_bf16_f32 v82, v88, v89
	v_cvt_pk_bf16_f32 v83, v90, v91
	global_store_dwordx4 v[96:97], v[80:83], off
	s_nop 0
	s_waitcnt vmcnt(7)
	v_cvt_f32_u32_e32 v80, v189
	v_cvt_f32_u32_e32 v81, v188
	v_mad_i64_i32 v[82:83], s[54:55], v98, s74, v[146:147]
	v_fmamk_f32 v80, v81, 0x2f800000, v80
	v_fmamk_f32 v80, v80, 0x3a800000, v158
	v_rsq_f32_e32 v80, v80
	v_lshl_add_u64 v[82:83], v[82:83], 0, v[148:149]
	v_mul_f32_e32 v188, 0xbfb8aa3b, v80
	v_mul_f32_e32 v189, v80, v80
	v_mul_f32_e32 v80, v76, v188
	v_mul_f32_e32 v81, v77, v188
	v_mul_f32_e32 v84, v78, v188
	v_mul_f32_e32 v85, v79, v188
	v_mul_f32_e32 v86, v72, v188
	v_mul_f32_e32 v87, v73, v188
	v_mul_f32_e32 v88, v74, v188
	v_mul_f32_e32 v89, v75, v188
	v_mul_f32_e32 v68, v68, v76
	v_mul_f32_e32 v69, v69, v77
	v_mul_f32_e32 v70, v70, v78
	v_mul_f32_e32 v71, v71, v79
	v_mul_f32_e32 v72, v64, v72
	v_mul_f32_e32 v73, v65, v73
	v_mul_f32_e32 v74, v66, v74
	v_mul_f32_e32 v75, v67, v75
	v_exp_f32_e32 v80, v80
	v_exp_f32_e32 v81, v81
	v_exp_f32_e32 v84, v84
	v_exp_f32_e32 v85, v85
	v_exp_f32_e32 v86, v86
	v_exp_f32_e32 v87, v87
	v_exp_f32_e32 v88, v88
	v_exp_f32_e32 v89, v89
	v_mul_f32_e32 v68, v68, v189
	v_mul_f32_e32 v69, v69, v189
	v_mul_f32_e32 v70, v70, v189
	v_mul_f32_e32 v71, v71, v189
	v_mul_f32_e32 v72, v72, v189
	v_mul_f32_e32 v73, v73, v189
	v_mul_f32_e32 v74, v74, v189
	v_mul_f32_e32 v75, v75, v189
	v_add_f32_e32 v80, 1.0, v80
	v_add_f32_e32 v81, 1.0, v81
	v_add_f32_e32 v84, 1.0, v84
	v_add_f32_e32 v85, 1.0, v85
	v_add_f32_e32 v86, 1.0, v86
	v_add_f32_e32 v87, 1.0, v87
	v_add_f32_e32 v88, 1.0, v88
	v_add_f32_e32 v89, 1.0, v89
	v_rcp_f32_e32 v80, v80
	v_rcp_f32_e32 v81, v81
	v_rcp_f32_e32 v84, v84
	v_rcp_f32_e32 v85, v85
	v_rcp_f32_e32 v86, v86
	v_rcp_f32_e32 v87, v87
	v_rcp_f32_e32 v88, v88
	v_rcp_f32_e32 v89, v89
	v_mul_f32_e32 v68, v68, v80
	v_mul_f32_e32 v69, v69, v81
	v_mul_f32_e32 v70, v70, v84
	v_mul_f32_e32 v71, v71, v85
	v_mul_f32_e32 v72, v72, v86
	v_mul_f32_e32 v73, v73, v87
	v_mul_f32_e32 v74, v74, v88
	v_mul_f32_e32 v75, v75, v89
	v_cvt_pk_bf16_f32 v64, v68, v69
	v_cvt_pk_bf16_f32 v65, v70, v71
	v_cvt_pk_bf16_f32 v66, v72, v73
	v_cvt_pk_bf16_f32 v67, v74, v75
	global_store_dwordx4 v[82:83], v[64:67], off
	s_nop 0
	s_waitcnt vmcnt(7)
	v_cvt_f32_u32_e32 v64, v191
	v_cvt_f32_u32_e32 v66, v190
	v_add_u32_e32 v65, 0x80, v144
	v_fmamk_f32 v64, v66, 0x2f800000, v64
	v_fmamk_f32 v64, v64, 0x3a800000, v158
	v_rsq_f32_e32 v64, v64
	v_mad_i64_i32 v[66:67], s[54:55], v65, s74, v[146:147]
	v_lshl_add_u64 v[66:67], v[66:67], 0, v[148:149]
	v_mul_f32_e32 v190, 0xbfb8aa3b, v64
	v_mul_f32_e32 v191, v64, v64
	v_mul_f32_e32 v64, v60, v190
	v_mul_f32_e32 v65, v61, v190
	v_mul_f32_e32 v68, v62, v190
	v_mul_f32_e32 v69, v63, v190
	v_mul_f32_e32 v70, v56, v190
	v_mul_f32_e32 v71, v57, v190
	v_mul_f32_e32 v72, v58, v190
	v_mul_f32_e32 v73, v59, v190
	v_mul_f32_e32 v52, v52, v60
	v_mul_f32_e32 v53, v53, v61
	v_mul_f32_e32 v54, v54, v62
	v_mul_f32_e32 v55, v55, v63
	v_mul_f32_e32 v56, v48, v56
	v_mul_f32_e32 v57, v49, v57
	v_mul_f32_e32 v58, v50, v58
	v_mul_f32_e32 v59, v51, v59
	v_exp_f32_e32 v64, v64
	v_exp_f32_e32 v65, v65
	v_exp_f32_e32 v68, v68
	v_exp_f32_e32 v69, v69
	v_exp_f32_e32 v70, v70
	v_exp_f32_e32 v71, v71
	v_exp_f32_e32 v72, v72
	v_exp_f32_e32 v73, v73
	v_mul_f32_e32 v52, v52, v191
	v_mul_f32_e32 v53, v53, v191
	v_mul_f32_e32 v54, v54, v191
	v_mul_f32_e32 v55, v55, v191
	v_mul_f32_e32 v56, v56, v191
	v_mul_f32_e32 v57, v57, v191
	v_mul_f32_e32 v58, v58, v191
	v_mul_f32_e32 v59, v59, v191
	v_add_f32_e32 v64, 1.0, v64
	v_add_f32_e32 v65, 1.0, v65
	v_add_f32_e32 v68, 1.0, v68
	v_add_f32_e32 v69, 1.0, v69
	v_add_f32_e32 v70, 1.0, v70
	v_add_f32_e32 v71, 1.0, v71
	v_add_f32_e32 v72, 1.0, v72
	v_add_f32_e32 v73, 1.0, v73
	v_rcp_f32_e32 v64, v64
	v_rcp_f32_e32 v65, v65
	v_rcp_f32_e32 v68, v68
	v_rcp_f32_e32 v69, v69
	v_rcp_f32_e32 v70, v70
	v_rcp_f32_e32 v71, v71
	v_rcp_f32_e32 v72, v72
	v_rcp_f32_e32 v73, v73
	v_mul_f32_e32 v52, v52, v64
	v_mul_f32_e32 v53, v53, v65
	v_mul_f32_e32 v54, v54, v68
	v_mul_f32_e32 v55, v55, v69
	v_mul_f32_e32 v56, v56, v70
	v_mul_f32_e32 v57, v57, v71
	v_mul_f32_e32 v58, v58, v72
	v_mul_f32_e32 v59, v59, v73
	v_cvt_pk_bf16_f32 v48, v52, v53
	v_cvt_pk_bf16_f32 v49, v54, v55
	v_cvt_pk_bf16_f32 v50, v56, v57
	v_cvt_pk_bf16_f32 v51, v58, v59
	global_store_dwordx4 v[66:67], v[48:51], off
	s_nop 0
	s_waitcnt vmcnt(7)
; __device__ __forceinline__ unsigned cvtpk(float lo, float hi) { f32x2v_ v = {lo, hi}; bf16x2v_ b = __builtin_convertvector(v, bf16x2v_); return __builtin_bit_cast(unsigned, b); }
; __device__ __forceinline__ float row_rs(const float* ssp, int row) { const unsigned long long v = ((const unsigned long long*)ssp)[row];
;     return __builtin_amdgcn_rsqf((float)v * (1.0f / 4294967296.0f) * (1.0f / 1024.0f) + RMS_EPS); }
;     __device__ __forceinline__ void operator()(const f32x4 (&acc)[2][2][4][2], const Unit& u, int wr, int wc, int fr, int fq) const {
;     ...
;             for (int m = 0; m < 4; ++m) { const int row = row0 + ai * HALF + m * 16; const float rs = row_rs(ss, row);
;                 float hv[8];
; #pragma unroll
;                 for (int n = 0; n < 2; ++n)
; #pragma unroll
;                     for (int i = 0; i < 4; ++i) { const float g = acc[ai][0][m][n][i] * rs, uu = acc[ai][1][m][n][i] * rs;
;                         hv[n * 4 + i] = g * __builtin_amdgcn_rcpf(1.0f + __expf(-g)) * uu; }
;                 u32x4 w; w.x = cvtpk(hv[0], hv[1]); w.y = cvtpk(hv[2], hv[3]); w.z = cvtpk(hv[4], hv[5]); w.w = cvtpk(hv[6], hv[7]);
;                 *(u32x4*)(H + (size_t)row * ldh + col0) = w; }
	v_cvt_f32_u32_e32 v48, v193
	v_cvt_f32_u32_e32 v50, v192
	v_add_u32_e32 v49, 0x90, v144
	v_fmamk_f32 v48, v50, 0x2f800000, v48
	v_fmamk_f32 v48, v48, 0x3a800000, v158
	v_rsq_f32_e32 v48, v48
	v_mad_i64_i32 v[50:51], s[54:55], v49, s74, v[146:147]
	v_lshl_add_u64 v[50:51], v[50:51], 0, v[148:149]
	v_mul_f32_e32 v192, 0xbfb8aa3b, v48
	v_mul_f32_e32 v193, v48, v48
	v_mul_f32_e32 v48, v44, v192
	v_mul_f32_e32 v49, v45, v192
	v_mul_f32_e32 v52, v46, v192
	v_mul_f32_e32 v53, v47, v192
	v_mul_f32_e32 v54, v40, v192
	v_mul_f32_e32 v55, v41, v192
	v_mul_f32_e32 v56, v42, v192
	v_mul_f32_e32 v57, v43, v192
	v_mul_f32_e32 v36, v36, v44
	v_mul_f32_e32 v37, v37, v45
	v_mul_f32_e32 v38, v38, v46
	v_mul_f32_e32 v39, v39, v47
	v_mul_f32_e32 v40, v32, v40
	v_mul_f32_e32 v41, v33, v41
	v_mul_f32_e32 v42, v34, v42
	v_mul_f32_e32 v43, v35, v43
	v_exp_f32_e32 v48, v48
	v_exp_f32_e32 v49, v49
	v_exp_f32_e32 v52, v52
	v_exp_f32_e32 v53, v53
	v_exp_f32_e32 v54, v54
	v_exp_f32_e32 v55, v55
	v_exp_f32_e32 v56, v56
	v_exp_f32_e32 v57, v57
	v_mul_f32_e32 v36, v36, v193
	v_mul_f32_e32 v37, v37, v193
	v_mul_f32_e32 v38, v38, v193
	v_mul_f32_e32 v39, v39, v193
	v_mul_f32_e32 v40, v40, v193
	v_mul_f32_e32 v41, v41, v193
	v_mul_f32_e32 v42, v42, v193
	v_mul_f32_e32 v43, v43, v193
	v_add_f32_e32 v48, 1.0, v48
	v_add_f32_e32 v49, 1.0, v49
	v_add_f32_e32 v52, 1.0, v52
	v_add_f32_e32 v53, 1.0, v53
	v_add_f32_e32 v54, 1.0, v54
	v_add_f32_e32 v55, 1.0, v55
	v_add_f32_e32 v56, 1.0, v56
	v_add_f32_e32 v57, 1.0, v57
	v_rcp_f32_e32 v48, v48
	v_rcp_f32_e32 v49, v49
	v_rcp_f32_e32 v52, v52
	v_rcp_f32_e32 v53, v53
	v_rcp_f32_e32 v54, v54
	v_rcp_f32_e32 v55, v55
	v_rcp_f32_e32 v56, v56
	v_rcp_f32_e32 v57, v57
	v_mul_f32_e32 v36, v36, v48
	v_mul_f32_e32 v37, v37, v49
	v_mul_f32_e32 v38, v38, v52
	v_mul_f32_e32 v39, v39, v53
	v_mul_f32_e32 v40, v40, v54
	v_mul_f32_e32 v41, v41, v55
	v_mul_f32_e32 v42, v42, v56
	v_mul_f32_e32 v43, v43, v57
	v_cvt_pk_bf16_f32 v32, v36, v37
	v_cvt_pk_bf16_f32 v33, v38, v39
	v_cvt_pk_bf16_f32 v34, v40, v41
	v_cvt_pk_bf16_f32 v35, v42, v43
	global_store_dwordx4 v[50:51], v[32:35], off
	s_nop 0
	s_waitcnt vmcnt(7)
	v_cvt_f32_u32_e32 v32, v195
	v_cvt_f32_u32_e32 v34, v194
	v_add_u32_e32 v33, 0xa0, v144
	v_fmamk_f32 v32, v34, 0x2f800000, v32
	v_fmamk_f32 v32, v32, 0x3a800000, v158
	v_rsq_f32_e32 v32, v32
	v_mad_i64_i32 v[34:35], s[54:55], v33, s74, v[146:147]
	v_lshl_add_u64 v[34:35], v[34:35], 0, v[148:149]
	v_mul_f32_e32 v194, 0xbfb8aa3b, v32
	v_mul_f32_e32 v195, v32, v32
	v_mul_f32_e32 v32, v28, v194
	v_mul_f32_e32 v33, v29, v194
	v_mul_f32_e32 v36, v30, v194
	v_mul_f32_e32 v37, v31, v194
	v_mul_f32_e32 v38, v24, v194
	v_mul_f32_e32 v39, v25, v194
	v_mul_f32_e32 v40, v26, v194
	v_mul_f32_e32 v41, v27, v194
	v_mul_f32_e32 v20, v20, v28
	v_mul_f32_e32 v21, v21, v29
	v_mul_f32_e32 v22, v22, v30
	v_mul_f32_e32 v23, v23, v31
	v_mul_f32_e32 v24, v16, v24
	v_mul_f32_e32 v25, v17, v25
	v_mul_f32_e32 v26, v18, v26
	v_mul_f32_e32 v27, v19, v27
	v_exp_f32_e32 v32, v32
	v_exp_f32_e32 v33, v33
	v_exp_f32_e32 v36, v36
	v_exp_f32_e32 v37, v37
	v_exp_f32_e32 v38, v38
	v_exp_f32_e32 v39, v39
	v_exp_f32_e32 v40, v40
	v_exp_f32_e32 v41, v41
	v_mul_f32_e32 v20, v20, v195
	v_mul_f32_e32 v21, v21, v195
	v_mul_f32_e32 v22, v22, v195
	v_mul_f32_e32 v23, v23, v195
	v_mul_f32_e32 v24, v24, v195
	v_mul_f32_e32 v25, v25, v195
	v_mul_f32_e32 v26, v26, v195
	v_mul_f32_e32 v27, v27, v195
	v_add_f32_e32 v32, 1.0, v32
	v_add_f32_e32 v33, 1.0, v33
	v_add_f32_e32 v36, 1.0, v36
	v_add_f32_e32 v37, 1.0, v37
	v_add_f32_e32 v38, 1.0, v38
	v_add_f32_e32 v39, 1.0, v39
	v_add_f32_e32 v40, 1.0, v40
	v_add_f32_e32 v41, 1.0, v41
	v_rcp_f32_e32 v32, v32
	v_rcp_f32_e32 v33, v33
	v_rcp_f32_e32 v36, v36
	v_rcp_f32_e32 v37, v37
	v_rcp_f32_e32 v38, v38
	v_rcp_f32_e32 v39, v39
	v_rcp_f32_e32 v40, v40
	v_rcp_f32_e32 v41, v41
	v_mul_f32_e32 v20, v20, v32
	v_mul_f32_e32 v21, v21, v33
	v_mul_f32_e32 v22, v22, v36
	v_mul_f32_e32 v23, v23, v37
	v_mul_f32_e32 v24, v24, v38
	v_mul_f32_e32 v25, v25, v39
	v_mul_f32_e32 v26, v26, v40
	v_mul_f32_e32 v27, v27, v41
	v_cvt_pk_bf16_f32 v16, v20, v21
	v_cvt_pk_bf16_f32 v17, v22, v23
	v_cvt_pk_bf16_f32 v18, v24, v25
	v_cvt_pk_bf16_f32 v19, v26, v27
	global_store_dwordx4 v[34:35], v[16:19], off
	s_nop 0
	s_waitcnt vmcnt(7)
	v_cvt_f32_u32_e32 v16, v197
	v_cvt_f32_u32_e32 v18, v196
	v_add_u32_e32 v17, 0xb0, v144
	v_fmamk_f32 v16, v18, 0x2f800000, v16
	v_fmamk_f32 v16, v16, 0x3a800000, v158
	v_rsq_f32_e32 v16, v16
	v_mad_i64_i32 v[18:19], s[54:55], v17, s74, v[146:147]
	v_lshl_add_u64 v[18:19], v[18:19], 0, v[148:149]
	v_mul_f32_e32 v196, 0xbfb8aa3b, v16
	v_mul_f32_e32 v197, v16, v16
	v_mul_f32_e32 v16, v12, v196
	v_mul_f32_e32 v17, v13, v196
	v_mul_f32_e32 v20, v14, v196
	v_mul_f32_e32 v21, v15, v196
	v_mul_f32_e32 v22, v8, v196
	v_mul_f32_e32 v23, v9, v196
	v_mul_f32_e32 v24, v10, v196
	v_mul_f32_e32 v25, v11, v196
	v_mul_f32_e32 v4, v4, v12
	v_mul_f32_e32 v5, v5, v13
	v_mul_f32_e32 v6, v6, v14
	v_mul_f32_e32 v7, v7, v15
	v_mul_f32_e32 v8, v0, v8
	v_mul_f32_e32 v9, v1, v9
	v_mul_f32_e32 v10, v2, v10
	v_mul_f32_e32 v11, v3, v11
	v_exp_f32_e32 v16, v16
	v_exp_f32_e32 v17, v17
	v_exp_f32_e32 v20, v20
	v_exp_f32_e32 v21, v21
	v_exp_f32_e32 v22, v22
	v_exp_f32_e32 v23, v23
	v_exp_f32_e32 v24, v24
	v_exp_f32_e32 v25, v25
	v_mul_f32_e32 v4, v4, v197
	v_mul_f32_e32 v5, v5, v197
	v_mul_f32_e32 v6, v6, v197
	v_mul_f32_e32 v7, v7, v197
	v_mul_f32_e32 v8, v8, v197
	v_mul_f32_e32 v9, v9, v197
	v_mul_f32_e32 v10, v10, v197
	v_mul_f32_e32 v11, v11, v197
	v_add_f32_e32 v16, 1.0, v16
	v_add_f32_e32 v17, 1.0, v17
	v_add_f32_e32 v20, 1.0, v20
	v_add_f32_e32 v21, 1.0, v21
	v_add_f32_e32 v22, 1.0, v22
	v_add_f32_e32 v23, 1.0, v23
	v_add_f32_e32 v24, 1.0, v24
	v_add_f32_e32 v25, 1.0, v25
	v_rcp_f32_e32 v16, v16
	v_rcp_f32_e32 v17, v17
	v_rcp_f32_e32 v20, v20
	v_rcp_f32_e32 v21, v21
	v_rcp_f32_e32 v22, v22
	v_rcp_f32_e32 v23, v23
	v_rcp_f32_e32 v24, v24
	v_rcp_f32_e32 v25, v25
	v_mul_f32_e32 v4, v4, v16
	v_mul_f32_e32 v5, v5, v17
	v_mul_f32_e32 v6, v6, v20
	v_mul_f32_e32 v7, v7, v21
	v_mul_f32_e32 v8, v8, v22
	v_mul_f32_e32 v9, v9, v23
	v_mul_f32_e32 v10, v10, v24
	v_mul_f32_e32 v11, v11, v25
	v_cvt_pk_bf16_f32 v0, v4, v5
	v_cvt_pk_bf16_f32 v1, v6, v7
	v_cvt_pk_bf16_f32 v2, v8, v9
	v_cvt_pk_bf16_f32 v3, v10, v11
	global_store_dwordx4 v[18:19], v[0:3], off
	s_cbranch_vccnz .LBB0_1115
	s_andn2_b64 vcc, exec, s[0:1]
	s_cbranch_vccnz .LBB0_1114
	s_barrier
	s_branch .LBB0_1114

; __device__ __forceinline__ unsigned cvtpk(float lo, float hi) { f32x2v_ v = {lo, hi}; bf16x2v_ b = __builtin_convertvector(v, bf16x2v_); return __builtin_bit_cast(unsigned, b); }
; __device__ __forceinline__ float row_rs(const float* ssp, int row) { const unsigned long long v = ((const unsigned long long*)ssp)[row];
;     return __builtin_amdgcn_rsqf((float)v * (1.0f / 4294967296.0f) * (1.0f / 1024.0f) + RMS_EPS); }
;     __device__ __forceinline__ void operator()(const f32x4 (&acc)[2][2][4][2], const Unit& u, int wr, int wc, int fr, int fq) const {
;     ...
;             for (int m = 0; m < 4; ++m) { const int row = row0 + ai * HALF + m * 16; const float rs = row_rs(ss, row);
;                 float hv[8];
; #pragma unroll
;                 for (int n = 0; n < 2; ++n)
; #pragma unroll
;                     for (int i = 0; i < 4; ++i) { const float g = acc[ai][0][m][n][i] * rs, uu = acc[ai][1][m][n][i] * rs;
;                         hv[n * 4 + i] = g * __builtin_amdgcn_rcpf(1.0f + __expf(-g)) * uu; }
;                 u32x4 w; w.x = cvtpk(hv[0], hv[1]); w.y = cvtpk(hv[2], hv[3]); w.z = cvtpk(hv[4], hv[5]); w.w = cvtpk(hv[6], hv[7]);
;                 *(u32x4*)(H + (size_t)row * ldh + col0) = w; }
.LBB0_1903:
	v_lshl_or_b32 v160, s52, 7, v154
	v_ashrrev_i32_e32 v161, 31, v160
	v_or_b32_e32 v164, 16, v144
	v_ashrrev_i32_e32 v165, 31, v164
	v_lshl_add_u64 v[166:167], v[164:165], 3, s[0:1]
	v_mov_b64_e32 v[146:147], s[20:21]
	v_mad_i64_i32 v[162:163], s[38:39], v144, s51, v[146:147]
	s_andn2_b64 vcc, exec, s[4:5]
	s_mov_b64 s[4:5], -1
	s_waitcnt vmcnt(7)
	v_cvt_f32_u32_e32 v159, v183
	v_cvt_f32_u32_e32 v145, v182
	v_lshlrev_b64 v[148:149], 1, v[160:161]
	v_lshl_add_u64 v[162:163], v[162:163], 0, v[148:149]
	v_fmamk_f32 v145, v145, 0x2f800000, v159
	v_fmamk_f32 v145, v145, 0x3a800000, v158
	v_rsq_f32_e32 v160, v145
	s_nop 0
	v_mul_f32_e32 v182, 0xbfb8aa3b, v160
	v_mul_f32_e32 v183, v160, v160
	v_mul_f32_e32 v160, v124, v182
	v_mul_f32_e32 v161, v125, v182
	v_mul_f32_e32 v168, v126, v182
	v_mul_f32_e32 v169, v127, v182
	v_mul_f32_e32 v170, v120, v182
	v_mul_f32_e32 v171, v121, v182
	v_mul_f32_e32 v172, v122, v182
	v_mul_f32_e32 v173, v123, v182
	v_mul_f32_e32 v116, v116, v124
	v_mul_f32_e32 v117, v117, v125
	v_mul_f32_e32 v118, v118, v126
	v_mul_f32_e32 v119, v119, v127
	v_mul_f32_e32 v120, v112, v120
	v_mul_f32_e32 v121, v113, v121
	v_mul_f32_e32 v122, v114, v122
	v_mul_f32_e32 v123, v115, v123
	v_exp_f32_e32 v160, v160
	v_exp_f32_e32 v161, v161
	v_exp_f32_e32 v168, v168
	v_exp_f32_e32 v169, v169
	v_exp_f32_e32 v170, v170
	v_exp_f32_e32 v171, v171
	v_exp_f32_e32 v172, v172
	v_exp_f32_e32 v173, v173
	v_mul_f32_e32 v116, v116, v183
	v_mul_f32_e32 v117, v117, v183
	v_mul_f32_e32 v118, v118, v183
	v_mul_f32_e32 v119, v119, v183
	v_mul_f32_e32 v120, v120, v183
	v_mul_f32_e32 v121, v121, v183
	v_mul_f32_e32 v122, v122, v183
	v_mul_f32_e32 v123, v123, v183
	v_add_f32_e32 v160, 1.0, v160
	v_add_f32_e32 v161, 1.0, v161
	v_add_f32_e32 v168, 1.0, v168
	v_add_f32_e32 v169, 1.0, v169
	v_add_f32_e32 v170, 1.0, v170
	v_add_f32_e32 v171, 1.0, v171
	v_add_f32_e32 v172, 1.0, v172
	v_add_f32_e32 v173, 1.0, v173
	v_rcp_f32_e32 v160, v160
	v_rcp_f32_e32 v161, v161
	v_rcp_f32_e32 v168, v168
	v_rcp_f32_e32 v169, v169
	v_rcp_f32_e32 v170, v170
	v_rcp_f32_e32 v171, v171
	v_rcp_f32_e32 v172, v172
	v_rcp_f32_e32 v173, v173
	v_mul_f32_e32 v116, v116, v160
	v_mul_f32_e32 v117, v117, v161
	v_mul_f32_e32 v118, v118, v168
	v_mul_f32_e32 v119, v119, v169
	v_mul_f32_e32 v120, v120, v170
	v_mul_f32_e32 v121, v121, v171
	v_mul_f32_e32 v122, v122, v172
	v_mul_f32_e32 v123, v123, v173
	v_cvt_pk_bf16_f32 v112, v116, v117
	v_cvt_pk_bf16_f32 v113, v118, v119
	v_cvt_pk_bf16_f32 v114, v120, v121
	v_cvt_pk_bf16_f32 v115, v122, v123
	global_store_dwordx4 v[162:163], v[112:115], off
	s_nop 0
	s_nop 0
	v_or_b32_e32 v114, 32, v144
	s_waitcnt vmcnt(7)
	v_cvt_f32_u32_e32 v116, v185
	v_cvt_f32_u32_e32 v115, v184
	v_mad_i64_i32 v[112:113], s[38:39], v164, s51, v[146:147]
	v_fmamk_f32 v115, v115, 0x2f800000, v116
	v_fmamk_f32 v115, v115, 0x3a800000, v158
	v_rsq_f32_e32 v116, v115
	v_ashrrev_i32_e32 v115, 31, v114
	v_lshl_add_u64 v[118:119], v[114:115], 3, s[0:1]
	v_lshl_add_u64 v[112:113], v[112:113], 0, v[148:149]
	v_mul_f32_e32 v184, 0xbfb8aa3b, v116
	v_mul_f32_e32 v185, v116, v116
	v_mul_f32_e32 v116, v108, v184
	v_mul_f32_e32 v117, v109, v184
	v_mul_f32_e32 v120, v110, v184
	v_mul_f32_e32 v121, v111, v184
	v_mul_f32_e32 v122, v104, v184
	v_mul_f32_e32 v123, v105, v184
	v_mul_f32_e32 v124, v106, v184
	v_mul_f32_e32 v125, v107, v184
	v_mul_f32_e32 v100, v100, v108
	v_mul_f32_e32 v101, v101, v109
	v_mul_f32_e32 v102, v102, v110
	v_mul_f32_e32 v103, v103, v111
	v_mul_f32_e32 v104, v96, v104
	v_mul_f32_e32 v105, v97, v105
	v_mul_f32_e32 v106, v98, v106
	v_mul_f32_e32 v107, v99, v107
	v_exp_f32_e32 v116, v116
	v_exp_f32_e32 v117, v117
	v_exp_f32_e32 v120, v120
	v_exp_f32_e32 v121, v121
	v_exp_f32_e32 v122, v122
	v_exp_f32_e32 v123, v123
	v_exp_f32_e32 v124, v124
	v_exp_f32_e32 v125, v125
	v_mul_f32_e32 v100, v100, v185
	v_mul_f32_e32 v101, v101, v185
	v_mul_f32_e32 v102, v102, v185
	v_mul_f32_e32 v103, v103, v185
	v_mul_f32_e32 v104, v104, v185
	v_mul_f32_e32 v105, v105, v185
	v_mul_f32_e32 v106, v106, v185
	v_mul_f32_e32 v107, v107, v185
	v_add_f32_e32 v116, 1.0, v116
	v_add_f32_e32 v117, 1.0, v117
	v_add_f32_e32 v120, 1.0, v120
	v_add_f32_e32 v121, 1.0, v121
	v_add_f32_e32 v122, 1.0, v122
	v_add_f32_e32 v123, 1.0, v123
	v_add_f32_e32 v124, 1.0, v124
	v_add_f32_e32 v125, 1.0, v125
	v_rcp_f32_e32 v116, v116
	v_rcp_f32_e32 v117, v117
	v_rcp_f32_e32 v120, v120
	v_rcp_f32_e32 v121, v121
	v_rcp_f32_e32 v122, v122
	v_rcp_f32_e32 v123, v123
	v_rcp_f32_e32 v124, v124
	v_rcp_f32_e32 v125, v125
	v_mul_f32_e32 v100, v100, v116
	v_mul_f32_e32 v101, v101, v117
	v_mul_f32_e32 v102, v102, v120
	v_mul_f32_e32 v103, v103, v121
	v_mul_f32_e32 v104, v104, v122
	v_mul_f32_e32 v105, v105, v123
	v_mul_f32_e32 v106, v106, v124
	v_mul_f32_e32 v107, v107, v125
	v_cvt_pk_bf16_f32 v96, v100, v101
	v_cvt_pk_bf16_f32 v97, v102, v103
	v_cvt_pk_bf16_f32 v98, v104, v105
	v_cvt_pk_bf16_f32 v99, v106, v107
	global_store_dwordx4 v[112:113], v[96:99], off
	s_nop 0
	s_nop 0
	v_or_b32_e32 v98, 48, v144
	s_waitcnt vmcnt(7)
; __device__ __forceinline__ unsigned cvtpk(float lo, float hi) { f32x2v_ v = {lo, hi}; bf16x2v_ b = __builtin_convertvector(v, bf16x2v_); return __builtin_bit_cast(unsigned, b); }
; __device__ __forceinline__ float row_rs(const float* ssp, int row) { const unsigned long long v = ((const unsigned long long*)ssp)[row];
;     return __builtin_amdgcn_rsqf((float)v * (1.0f / 4294967296.0f) * (1.0f / 1024.0f) + RMS_EPS); }
;     __device__ __forceinline__ void operator()(const f32x4 (&acc)[2][2][4][2], const Unit& u, int wr, int wc, int fr, int fq) const {
;     ...
;             for (int m = 0; m < 4; ++m) { const int row = row0 + ai * HALF + m * 16; const float rs = row_rs(ss, row);
;                 float hv[8];
; #pragma unroll
;                 for (int n = 0; n < 2; ++n)
; #pragma unroll
;                     for (int i = 0; i < 4; ++i) { const float g = acc[ai][0][m][n][i] * rs, uu = acc[ai][1][m][n][i] * rs;
;                         hv[n * 4 + i] = g * __builtin_amdgcn_rcpf(1.0f + __expf(-g)) * uu; }
;                 u32x4 w; w.x = cvtpk(hv[0], hv[1]); w.y = cvtpk(hv[2], hv[3]); w.z = cvtpk(hv[4], hv[5]); w.w = cvtpk(hv[6], hv[7]);
;                 *(u32x4*)(H + (size_t)row * ldh + col0) = w; }
	v_cvt_f32_u32_e32 v100, v187
	v_cvt_f32_u32_e32 v99, v186
	v_mad_i64_i32 v[96:97], s[38:39], v114, s51, v[146:147]
	v_fmamk_f32 v99, v99, 0x2f800000, v100
	v_fmamk_f32 v99, v99, 0x3a800000, v158
	v_rsq_f32_e32 v100, v99
	v_ashrrev_i32_e32 v99, 31, v98
	v_lshl_add_u64 v[102:103], v[98:99], 3, s[0:1]
	v_lshl_add_u64 v[96:97], v[96:97], 0, v[148:149]
	v_mul_f32_e32 v186, 0xbfb8aa3b, v100
	v_mul_f32_e32 v187, v100, v100
	v_mul_f32_e32 v100, v92, v186
	v_mul_f32_e32 v101, v93, v186
	v_mul_f32_e32 v104, v94, v186
	v_mul_f32_e32 v105, v95, v186
	v_mul_f32_e32 v106, v88, v186
	v_mul_f32_e32 v107, v89, v186
	v_mul_f32_e32 v108, v90, v186
	v_mul_f32_e32 v109, v91, v186
	v_mul_f32_e32 v84, v84, v92
	v_mul_f32_e32 v85, v85, v93
	v_mul_f32_e32 v86, v86, v94
	v_mul_f32_e32 v87, v87, v95
	v_mul_f32_e32 v88, v80, v88
	v_mul_f32_e32 v89, v81, v89
	v_mul_f32_e32 v90, v82, v90
	v_mul_f32_e32 v91, v83, v91
	v_exp_f32_e32 v100, v100
	v_exp_f32_e32 v101, v101
	v_exp_f32_e32 v104, v104
	v_exp_f32_e32 v105, v105
	v_exp_f32_e32 v106, v106
	v_exp_f32_e32 v107, v107
	v_exp_f32_e32 v108, v108
	v_exp_f32_e32 v109, v109
	v_mul_f32_e32 v84, v84, v187
	v_mul_f32_e32 v85, v85, v187
	v_mul_f32_e32 v86, v86, v187
	v_mul_f32_e32 v87, v87, v187
	v_mul_f32_e32 v88, v88, v187
	v_mul_f32_e32 v89, v89, v187
	v_mul_f32_e32 v90, v90, v187
	v_mul_f32_e32 v91, v91, v187
	v_add_f32_e32 v100, 1.0, v100
	v_add_f32_e32 v101, 1.0, v101
	v_add_f32_e32 v104, 1.0, v104
	v_add_f32_e32 v105, 1.0, v105
	v_add_f32_e32 v106, 1.0, v106
	v_add_f32_e32 v107, 1.0, v107
	v_add_f32_e32 v108, 1.0, v108
	v_add_f32_e32 v109, 1.0, v109
	v_rcp_f32_e32 v100, v100
	v_rcp_f32_e32 v101, v101
	v_rcp_f32_e32 v104, v104
	v_rcp_f32_e32 v105, v105
	v_rcp_f32_e32 v106, v106
	v_rcp_f32_e32 v107, v107
	v_rcp_f32_e32 v108, v108
	v_rcp_f32_e32 v109, v109
	v_mul_f32_e32 v84, v84, v100
	v_mul_f32_e32 v85, v85, v101
	v_mul_f32_e32 v86, v86, v104
	v_mul_f32_e32 v87, v87, v105
	v_mul_f32_e32 v88, v88, v106
	v_mul_f32_e32 v89, v89, v107
	v_mul_f32_e32 v90, v90, v108
	v_mul_f32_e32 v91, v91, v109
	v_cvt_pk_bf16_f32 v80, v84, v85
	v_cvt_pk_bf16_f32 v81, v86, v87
	v_cvt_pk_bf16_f32 v82, v88, v89
	v_cvt_pk_bf16_f32 v83, v90, v91
	global_store_dwordx4 v[96:97], v[80:83], off
	s_nop 0
	s_waitcnt vmcnt(7)
	v_cvt_f32_u32_e32 v80, v189
	v_cvt_f32_u32_e32 v81, v188
	v_mad_i64_i32 v[82:83], s[38:39], v98, s51, v[146:147]
	v_fmamk_f32 v80, v81, 0x2f800000, v80
	v_fmamk_f32 v80, v80, 0x3a800000, v158
	v_rsq_f32_e32 v80, v80
	v_lshl_add_u64 v[82:83], v[82:83], 0, v[148:149]
	v_mul_f32_e32 v188, 0xbfb8aa3b, v80
	v_mul_f32_e32 v189, v80, v80
	v_mul_f32_e32 v80, v76, v188
	v_mul_f32_e32 v81, v77, v188
	v_mul_f32_e32 v84, v78, v188
	v_mul_f32_e32 v85, v79, v188
	v_mul_f32_e32 v86, v72, v188
	v_mul_f32_e32 v87, v73, v188
	v_mul_f32_e32 v88, v74, v188
	v_mul_f32_e32 v89, v75, v188
	v_mul_f32_e32 v68, v68, v76
	v_mul_f32_e32 v69, v69, v77
	v_mul_f32_e32 v70, v70, v78
	v_mul_f32_e32 v71, v71, v79
	v_mul_f32_e32 v72, v64, v72
	v_mul_f32_e32 v73, v65, v73
	v_mul_f32_e32 v74, v66, v74
	v_mul_f32_e32 v75, v67, v75
	v_exp_f32_e32 v80, v80
	v_exp_f32_e32 v81, v81
	v_exp_f32_e32 v84, v84
	v_exp_f32_e32 v85, v85
	v_exp_f32_e32 v86, v86
	v_exp_f32_e32 v87, v87
	v_exp_f32_e32 v88, v88
	v_exp_f32_e32 v89, v89
	v_mul_f32_e32 v68, v68, v189
	v_mul_f32_e32 v69, v69, v189
	v_mul_f32_e32 v70, v70, v189
	v_mul_f32_e32 v71, v71, v189
	v_mul_f32_e32 v72, v72, v189
	v_mul_f32_e32 v73, v73, v189
	v_mul_f32_e32 v74, v74, v189
	v_mul_f32_e32 v75, v75, v189
	v_add_f32_e32 v80, 1.0, v80
	v_add_f32_e32 v81, 1.0, v81
	v_add_f32_e32 v84, 1.0, v84
	v_add_f32_e32 v85, 1.0, v85
	v_add_f32_e32 v86, 1.0, v86
	v_add_f32_e32 v87, 1.0, v87
	v_add_f32_e32 v88, 1.0, v88
	v_add_f32_e32 v89, 1.0, v89
	v_rcp_f32_e32 v80, v80
	v_rcp_f32_e32 v81, v81
	v_rcp_f32_e32 v84, v84
	v_rcp_f32_e32 v85, v85
	v_rcp_f32_e32 v86, v86
	v_rcp_f32_e32 v87, v87
	v_rcp_f32_e32 v88, v88
	v_rcp_f32_e32 v89, v89
	v_mul_f32_e32 v68, v68, v80
	v_mul_f32_e32 v69, v69, v81
	v_mul_f32_e32 v70, v70, v84
	v_mul_f32_e32 v71, v71, v85
	v_mul_f32_e32 v72, v72, v86
	v_mul_f32_e32 v73, v73, v87
	v_mul_f32_e32 v74, v74, v88
	v_mul_f32_e32 v75, v75, v89
	v_cvt_pk_bf16_f32 v64, v68, v69
	v_cvt_pk_bf16_f32 v65, v70, v71
	v_cvt_pk_bf16_f32 v66, v72, v73
	v_cvt_pk_bf16_f32 v67, v74, v75
	global_store_dwordx4 v[82:83], v[64:67], off
	s_nop 0
	s_waitcnt vmcnt(7)
	v_cvt_f32_u32_e32 v64, v191
	v_cvt_f32_u32_e32 v66, v190
	v_add_u32_e32 v65, 0x80, v144
	v_fmamk_f32 v64, v66, 0x2f800000, v64
	v_fmamk_f32 v64, v64, 0x3a800000, v158
	v_rsq_f32_e32 v64, v64
	v_mad_i64_i32 v[66:67], s[38:39], v65, s51, v[146:147]
	v_lshl_add_u64 v[66:67], v[66:67], 0, v[148:149]
	v_mul_f32_e32 v190, 0xbfb8aa3b, v64
	v_mul_f32_e32 v191, v64, v64
	v_mul_f32_e32 v64, v60, v190
	v_mul_f32_e32 v65, v61, v190
	v_mul_f32_e32 v68, v62, v190
	v_mul_f32_e32 v69, v63, v190
	v_mul_f32_e32 v70, v56, v190
	v_mul_f32_e32 v71, v57, v190
	v_mul_f32_e32 v72, v58, v190
	v_mul_f32_e32 v73, v59, v190
	v_mul_f32_e32 v52, v52, v60
	v_mul_f32_e32 v53, v53, v61
	v_mul_f32_e32 v54, v54, v62
	v_mul_f32_e32 v55, v55, v63
	v_mul_f32_e32 v56, v48, v56
	v_mul_f32_e32 v57, v49, v57
	v_mul_f32_e32 v58, v50, v58
	v_mul_f32_e32 v59, v51, v59
	v_exp_f32_e32 v64, v64
	v_exp_f32_e32 v65, v65
	v_exp_f32_e32 v68, v68
	v_exp_f32_e32 v69, v69
	v_exp_f32_e32 v70, v70
	v_exp_f32_e32 v71, v71
	v_exp_f32_e32 v72, v72
	v_exp_f32_e32 v73, v73
	v_mul_f32_e32 v52, v52, v191
	v_mul_f32_e32 v53, v53, v191
	v_mul_f32_e32 v54, v54, v191
	v_mul_f32_e32 v55, v55, v191
	v_mul_f32_e32 v56, v56, v191
	v_mul_f32_e32 v57, v57, v191
	v_mul_f32_e32 v58, v58, v191
	v_mul_f32_e32 v59, v59, v191
	v_add_f32_e32 v64, 1.0, v64
	v_add_f32_e32 v65, 1.0, v65
	v_add_f32_e32 v68, 1.0, v68
	v_add_f32_e32 v69, 1.0, v69
	v_add_f32_e32 v70, 1.0, v70
	v_add_f32_e32 v71, 1.0, v71
	v_add_f32_e32 v72, 1.0, v72
	v_add_f32_e32 v73, 1.0, v73
	v_rcp_f32_e32 v64, v64
	v_rcp_f32_e32 v65, v65
	v_rcp_f32_e32 v68, v68
	v_rcp_f32_e32 v69, v69
	v_rcp_f32_e32 v70, v70
	v_rcp_f32_e32 v71, v71
	v_rcp_f32_e32 v72, v72
	v_rcp_f32_e32 v73, v73
	v_mul_f32_e32 v52, v52, v64
	v_mul_f32_e32 v53, v53, v65
	v_mul_f32_e32 v54, v54, v68
	v_mul_f32_e32 v55, v55, v69
	v_mul_f32_e32 v56, v56, v70
	v_mul_f32_e32 v57, v57, v71
	v_mul_f32_e32 v58, v58, v72
	v_mul_f32_e32 v59, v59, v73
	v_cvt_pk_bf16_f32 v48, v52, v53
	v_cvt_pk_bf16_f32 v49, v54, v55
	v_cvt_pk_bf16_f32 v50, v56, v57
	v_cvt_pk_bf16_f32 v51, v58, v59
	global_store_dwordx4 v[66:67], v[48:51], off
	s_nop 0
	s_waitcnt vmcnt(7)
; __device__ __forceinline__ unsigned cvtpk(float lo, float hi) { f32x2v_ v = {lo, hi}; bf16x2v_ b = __builtin_convertvector(v, bf16x2v_); return __builtin_bit_cast(unsigned, b); }
; __device__ __forceinline__ float row_rs(const float* ssp, int row) { const unsigned long long v = ((const unsigned long long*)ssp)[row];
;     return __builtin_amdgcn_rsqf((float)v * (1.0f / 4294967296.0f) * (1.0f / 1024.0f) + RMS_EPS); }
;     __device__ __forceinline__ void operator()(const f32x4 (&acc)[2][2][4][2], const Unit& u, int wr, int wc, int fr, int fq) const {
;     ...
;             for (int m = 0; m < 4; ++m) { const int row = row0 + ai * HALF + m * 16; const float rs = row_rs(ss, row);
;                 float hv[8];
; #pragma unroll
;                 for (int n = 0; n < 2; ++n)
; #pragma unroll
;                     for (int i = 0; i < 4; ++i) { const float g = acc[ai][0][m][n][i] * rs, uu = acc[ai][1][m][n][i] * rs;
;                         hv[n * 4 + i] = g * __builtin_amdgcn_rcpf(1.0f + __expf(-g)) * uu; }
;                 u32x4 w; w.x = cvtpk(hv[0], hv[1]); w.y = cvtpk(hv[2], hv[3]); w.z = cvtpk(hv[4], hv[5]); w.w = cvtpk(hv[6], hv[7]);
;                 *(u32x4*)(H + (size_t)row * ldh + col0) = w; }
	v_cvt_f32_u32_e32 v48, v193
	v_cvt_f32_u32_e32 v50, v192
	v_add_u32_e32 v49, 0x90, v144
	v_fmamk_f32 v48, v50, 0x2f800000, v48
	v_fmamk_f32 v48, v48, 0x3a800000, v158
	v_rsq_f32_e32 v48, v48
	v_mad_i64_i32 v[50:51], s[38:39], v49, s51, v[146:147]
	v_lshl_add_u64 v[50:51], v[50:51], 0, v[148:149]
	v_mul_f32_e32 v192, 0xbfb8aa3b, v48
	v_mul_f32_e32 v193, v48, v48
	v_mul_f32_e32 v48, v44, v192
	v_mul_f32_e32 v49, v45, v192
	v_mul_f32_e32 v52, v46, v192
	v_mul_f32_e32 v53, v47, v192
	v_mul_f32_e32 v54, v40, v192
	v_mul_f32_e32 v55, v41, v192
	v_mul_f32_e32 v56, v42, v192
	v_mul_f32_e32 v57, v43, v192
	v_mul_f32_e32 v36, v36, v44
	v_mul_f32_e32 v37, v37, v45
	v_mul_f32_e32 v38, v38, v46
	v_mul_f32_e32 v39, v39, v47
	v_mul_f32_e32 v40, v32, v40
	v_mul_f32_e32 v41, v33, v41
	v_mul_f32_e32 v42, v34, v42
	v_mul_f32_e32 v43, v35, v43
	v_exp_f32_e32 v48, v48
	v_exp_f32_e32 v49, v49
	v_exp_f32_e32 v52, v52
	v_exp_f32_e32 v53, v53
	v_exp_f32_e32 v54, v54
	v_exp_f32_e32 v55, v55
	v_exp_f32_e32 v56, v56
	v_exp_f32_e32 v57, v57
	v_mul_f32_e32 v36, v36, v193
	v_mul_f32_e32 v37, v37, v193
	v_mul_f32_e32 v38, v38, v193
	v_mul_f32_e32 v39, v39, v193
	v_mul_f32_e32 v40, v40, v193
	v_mul_f32_e32 v41, v41, v193
	v_mul_f32_e32 v42, v42, v193
	v_mul_f32_e32 v43, v43, v193
	v_add_f32_e32 v48, 1.0, v48
	v_add_f32_e32 v49, 1.0, v49
	v_add_f32_e32 v52, 1.0, v52
	v_add_f32_e32 v53, 1.0, v53
	v_add_f32_e32 v54, 1.0, v54
	v_add_f32_e32 v55, 1.0, v55
	v_add_f32_e32 v56, 1.0, v56
	v_add_f32_e32 v57, 1.0, v57
	v_rcp_f32_e32 v48, v48
	v_rcp_f32_e32 v49, v49
	v_rcp_f32_e32 v52, v52
	v_rcp_f32_e32 v53, v53
	v_rcp_f32_e32 v54, v54
	v_rcp_f32_e32 v55, v55
	v_rcp_f32_e32 v56, v56
	v_rcp_f32_e32 v57, v57
	v_mul_f32_e32 v36, v36, v48
	v_mul_f32_e32 v37, v37, v49
	v_mul_f32_e32 v38, v38, v52
	v_mul_f32_e32 v39, v39, v53
	v_mul_f32_e32 v40, v40, v54
	v_mul_f32_e32 v41, v41, v55
	v_mul_f32_e32 v42, v42, v56
	v_mul_f32_e32 v43, v43, v57
	v_cvt_pk_bf16_f32 v32, v36, v37
	v_cvt_pk_bf16_f32 v33, v38, v39
	v_cvt_pk_bf16_f32 v34, v40, v41
	v_cvt_pk_bf16_f32 v35, v42, v43
	global_store_dwordx4 v[50:51], v[32:35], off
	s_nop 0
	s_waitcnt vmcnt(7)
	v_cvt_f32_u32_e32 v32, v195
	v_cvt_f32_u32_e32 v34, v194
	v_add_u32_e32 v33, 0xa0, v144
	v_fmamk_f32 v32, v34, 0x2f800000, v32
	v_fmamk_f32 v32, v32, 0x3a800000, v158
	v_rsq_f32_e32 v32, v32
	v_mad_i64_i32 v[34:35], s[38:39], v33, s51, v[146:147]
	v_lshl_add_u64 v[34:35], v[34:35], 0, v[148:149]
	v_mul_f32_e32 v194, 0xbfb8aa3b, v32
	v_mul_f32_e32 v195, v32, v32
	v_mul_f32_e32 v32, v28, v194
	v_mul_f32_e32 v33, v29, v194
	v_mul_f32_e32 v36, v30, v194
	v_mul_f32_e32 v37, v31, v194
	v_mul_f32_e32 v38, v24, v194
	v_mul_f32_e32 v39, v25, v194
	v_mul_f32_e32 v40, v26, v194
	v_mul_f32_e32 v41, v27, v194
	v_mul_f32_e32 v20, v20, v28
	v_mul_f32_e32 v21, v21, v29
	v_mul_f32_e32 v22, v22, v30
	v_mul_f32_e32 v23, v23, v31
	v_mul_f32_e32 v24, v16, v24
	v_mul_f32_e32 v25, v17, v25
	v_mul_f32_e32 v26, v18, v26
	v_mul_f32_e32 v27, v19, v27
	v_exp_f32_e32 v32, v32
	v_exp_f32_e32 v33, v33
	v_exp_f32_e32 v36, v36
	v_exp_f32_e32 v37, v37
	v_exp_f32_e32 v38, v38
	v_exp_f32_e32 v39, v39
	v_exp_f32_e32 v40, v40
	v_exp_f32_e32 v41, v41
	v_mul_f32_e32 v20, v20, v195
	v_mul_f32_e32 v21, v21, v195
	v_mul_f32_e32 v22, v22, v195
	v_mul_f32_e32 v23, v23, v195
	v_mul_f32_e32 v24, v24, v195
	v_mul_f32_e32 v25, v25, v195
	v_mul_f32_e32 v26, v26, v195
	v_mul_f32_e32 v27, v27, v195
	v_add_f32_e32 v32, 1.0, v32
	v_add_f32_e32 v33, 1.0, v33
	v_add_f32_e32 v36, 1.0, v36
	v_add_f32_e32 v37, 1.0, v37
	v_add_f32_e32 v38, 1.0, v38
	v_add_f32_e32 v39, 1.0, v39
	v_add_f32_e32 v40, 1.0, v40
	v_add_f32_e32 v41, 1.0, v41
	v_rcp_f32_e32 v32, v32
	v_rcp_f32_e32 v33, v33
	v_rcp_f32_e32 v36, v36
	v_rcp_f32_e32 v37, v37
	v_rcp_f32_e32 v38, v38
	v_rcp_f32_e32 v39, v39
	v_rcp_f32_e32 v40, v40
	v_rcp_f32_e32 v41, v41
	v_mul_f32_e32 v20, v20, v32
	v_mul_f32_e32 v21, v21, v33
	v_mul_f32_e32 v22, v22, v36
	v_mul_f32_e32 v23, v23, v37
	v_mul_f32_e32 v24, v24, v38
	v_mul_f32_e32 v25, v25, v39
	v_mul_f32_e32 v26, v26, v40
	v_mul_f32_e32 v27, v27, v41
	v_cvt_pk_bf16_f32 v16, v20, v21
	v_cvt_pk_bf16_f32 v17, v22, v23
	v_cvt_pk_bf16_f32 v18, v24, v25
	v_cvt_pk_bf16_f32 v19, v26, v27
	global_store_dwordx4 v[34:35], v[16:19], off
	s_nop 0
	s_waitcnt vmcnt(7)
	v_cvt_f32_u32_e32 v16, v197
	v_cvt_f32_u32_e32 v18, v196
	v_add_u32_e32 v17, 0xb0, v144
	v_fmamk_f32 v16, v18, 0x2f800000, v16
	v_fmamk_f32 v16, v16, 0x3a800000, v158
	v_rsq_f32_e32 v16, v16
	v_mad_i64_i32 v[18:19], s[38:39], v17, s51, v[146:147]
	v_lshl_add_u64 v[18:19], v[18:19], 0, v[148:149]
	v_mul_f32_e32 v196, 0xbfb8aa3b, v16
	v_mul_f32_e32 v197, v16, v16
	v_mul_f32_e32 v16, v12, v196
	v_mul_f32_e32 v17, v13, v196
	v_mul_f32_e32 v20, v14, v196
	v_mul_f32_e32 v21, v15, v196
	v_mul_f32_e32 v22, v8, v196
	v_mul_f32_e32 v23, v9, v196
	v_mul_f32_e32 v24, v10, v196
	v_mul_f32_e32 v25, v11, v196
	v_mul_f32_e32 v4, v4, v12
	v_mul_f32_e32 v5, v5, v13
	v_mul_f32_e32 v6, v6, v14
	v_mul_f32_e32 v7, v7, v15
	v_mul_f32_e32 v8, v0, v8
	v_mul_f32_e32 v9, v1, v9
	v_mul_f32_e32 v10, v2, v10
	v_mul_f32_e32 v11, v3, v11
	v_exp_f32_e32 v16, v16
	v_exp_f32_e32 v17, v17
	v_exp_f32_e32 v20, v20
	v_exp_f32_e32 v21, v21
	v_exp_f32_e32 v22, v22
	v_exp_f32_e32 v23, v23
	v_exp_f32_e32 v24, v24
	v_exp_f32_e32 v25, v25
	v_mul_f32_e32 v4, v4, v197
	v_mul_f32_e32 v5, v5, v197
	v_mul_f32_e32 v6, v6, v197
	v_mul_f32_e32 v7, v7, v197
	v_mul_f32_e32 v8, v8, v197
	v_mul_f32_e32 v9, v9, v197
	v_mul_f32_e32 v10, v10, v197
	v_mul_f32_e32 v11, v11, v197
	v_add_f32_e32 v16, 1.0, v16
	v_add_f32_e32 v17, 1.0, v17
	v_add_f32_e32 v20, 1.0, v20
	v_add_f32_e32 v21, 1.0, v21
	v_add_f32_e32 v22, 1.0, v22
	v_add_f32_e32 v23, 1.0, v23
	v_add_f32_e32 v24, 1.0, v24
	v_add_f32_e32 v25, 1.0, v25
	v_rcp_f32_e32 v16, v16
	v_rcp_f32_e32 v17, v17
	v_rcp_f32_e32 v20, v20
	v_rcp_f32_e32 v21, v21
	v_rcp_f32_e32 v22, v22
	v_rcp_f32_e32 v23, v23
	v_rcp_f32_e32 v24, v24
	v_rcp_f32_e32 v25, v25
	v_mul_f32_e32 v4, v4, v16
	v_mul_f32_e32 v5, v5, v17
	v_mul_f32_e32 v6, v6, v20
	v_mul_f32_e32 v7, v7, v21
	v_mul_f32_e32 v8, v8, v22
	v_mul_f32_e32 v9, v9, v23
	v_mul_f32_e32 v10, v10, v24
	v_mul_f32_e32 v11, v11, v25
	v_cvt_pk_bf16_f32 v0, v4, v5
	v_cvt_pk_bf16_f32 v1, v6, v7
	v_cvt_pk_bf16_f32 v2, v8, v9
	v_cvt_pk_bf16_f32 v3, v10, v11
	global_store_dwordx4 v[18:19], v[0:3], off
	s_cbranch_vccnz .LBB0_1896
	s_andn2_b64 vcc, exec, s[6:7]
	s_cbranch_vccnz .LBB0_1895
	s_barrier
	s_branch .LBB0_1895
